# KHEAD epilogue: all 8 row groups k_pe loads issued up front (stride from group 0 address), counted vmcnt waits instead of vmcnt(0) per group
# speedup vs baseline: 1.1554x; 1.0002x over previous
.LBB0_618:
	s_lshl_b32 s2, s4, 9
	v_bfe_u32 v149, v150, 4, 2
	s_add_i32 s64, s60, s2
	v_and_b32_e32 v130, 15, v150
	v_ashrrev_i32_e32 v131, 1, v150
	s_addk_i32 s64, 0xf800
	v_lshlrev_b32_e32 v142, 3, v149
	v_and_or_b32 v147, v131, s51, v130
	v_mov_b32_e32 v194, 0x0
	v_bfe_u32 v196, v0, 4, 2
	v_lshlrev_b32_e32 v196, 4, v196
	v_add_u32_e32 v194, v194, v196
	v_mov_b32_e32 v195, 0x100
	v_bfe_u32 v196, v0, 4, 2
	v_lshlrev_b32_e32 v196, 5, v196
	v_add_u32_e32 v195, v195, v196
	global_load_dwordx4 v[170:173], v194, s[20:21]
	global_load_dwordx4 v[174:177], v194, s[20:21] offset:64
	global_load_dwordx4 v[178:181], v194, s[20:21] offset:128
	global_load_dwordx4 v[182:185], v194, s[20:21] offset:192
	global_load_dwordx4 v[186:189], v195, s[20:21]
	global_load_dwordx4 v[190:193], v195, s[20:21] offset:16
	s_mov_b64 s[2:3], -1
	s_cmp_gt_i32 s62, 1
	v_lshlrev_b32_e32 v138, 2, v142
	s_cbranch_scc0 .LBB0_620
	v_add_u32_e32 v130, s64, v147
	v_ashrrev_i32_e32 v131, 31, v130
	v_lshlrev_b64 v[130:131], 7, v[130:131]
	v_lshl_add_u64 v[130:131], s[22:23], 0, v[130:131]
	v_mov_b32_e32 v139, v163
	v_lshl_add_u64 v[130:131], v[130:131], 0, v[138:139]
	v_mov_b32_e32 v164, v130
	v_mov_b32_e32 v165, v131
	global_load_dwordx4 v[134:137], v[130:131], off offset:16
	s_nop 0
	global_load_dwordx4 v[130:133], v[130:131], off
	s_mov_b64 s[2:3], 0x1000
	global_load_dwordx4 v[198:201], v[164:165], off offset:2064
	global_load_dwordx4 v[152:155], v[164:165], off offset:2048
	v_lshl_add_u64 v[164:165], v[164:165], 0, s[2:3]
	global_load_dwordx4 v[206:209], v[164:165], off offset:16
	global_load_dwordx4 v[202:205], v[164:165], off
	global_load_dwordx4 v[214:217], v[164:165], off offset:2064
	global_load_dwordx4 v[210:213], v[164:165], off offset:2048
	v_lshl_add_u64 v[164:165], v[164:165], 0, s[2:3]
	global_load_dwordx4 v[226:229], v[164:165], off offset:16
	global_load_dwordx4 v[218:221], v[164:165], off
	global_load_dwordx4 v[234:237], v[164:165], off offset:2064
	global_load_dwordx4 v[230:233], v[164:165], off offset:2048
	v_lshl_add_u64 v[164:165], v[164:165], 0, s[2:3]
	global_load_dwordx4 v[242:245], v[164:165], off offset:16
	global_load_dwordx4 v[238:241], v[164:165], off
	global_load_dwordx4 v[250:253], v[164:165], off offset:2064
	global_load_dwordx4 v[246:249], v[164:165], off offset:2048
	s_mov_b64 s[2:3], 0
.LBB0_620:
	s_lshl_b32 s4, s4, 11
	s_add_i32 s63, s60, s4
	s_addk_i32 s63, 0x2000
	s_andn2_b64 vcc, exec, s[2:3]
	v_add_u32_e32 v139, s61, v147
	s_cbranch_vccnz .LBB0_624
	s_cmp_lg_u32 s62, 0
	v_mov_b32_e32 v130, v139
	s_cbranch_scc0 .LBB0_623
	v_add_u32_e32 v130, s63, v147
.LBB0_623:
	v_mov_b64_e32 v[132:133], s[14:15]
	v_mad_i64_i32 v[130:131], s[2:3], v130, s54, v[132:133]
	v_lshlrev_b32_e32 v162, 1, v142
	v_lshl_add_u64 v[130:131], v[130:131], 0, v[162:163]
	global_load_dwordx4 v[134:137], v[130:131], off offset:768
	v_mov_b32_e32 v164, v130
	v_mov_b32_e32 v165, v131
	s_mov_b64 s[2:3], 0x11400
	v_lshl_add_u64 v[164:165], v[164:165], 0, s[2:3]
	global_load_dwordx4 v[198:201], v[164:165], off offset:768
	v_lshl_add_u64 v[164:165], v[164:165], 0, s[2:3]
	global_load_dwordx4 v[206:209], v[164:165], off offset:768
	v_lshl_add_u64 v[164:165], v[164:165], 0, s[2:3]
	global_load_dwordx4 v[214:217], v[164:165], off offset:768
	v_lshl_add_u64 v[164:165], v[164:165], 0, s[2:3]
	global_load_dwordx4 v[226:229], v[164:165], off offset:768
	v_lshl_add_u64 v[164:165], v[164:165], 0, s[2:3]
	global_load_dwordx4 v[234:237], v[164:165], off offset:768
	v_lshl_add_u64 v[164:165], v[164:165], 0, s[2:3]
	global_load_dwordx4 v[242:245], v[164:165], off offset:768
	v_lshl_add_u64 v[164:165], v[164:165], 0, s[2:3]
	global_load_dwordx4 v[250:253], v[164:165], off offset:768
	s_waitcnt vmcnt(7)
	v_lshlrev_b32_e32 v130, 16, v134
	v_and_b32_e32 v131, 0xffff0000, v134
	v_lshlrev_b32_e32 v132, 16, v135
	v_and_b32_e32 v133, 0xffff0000, v135
	v_lshlrev_b32_e32 v134, 16, v136
	v_and_b32_e32 v135, 0xffff0000, v136
	v_lshlrev_b32_e32 v136, 16, v137
	v_and_b32_e32 v137, 0xffff0000, v137
.LBB0_624:
	v_lshlrev_b32_e32 v162, 4, v149
	v_mul_f32_e32 v167, v127, v127
	v_fmac_f32_e32 v167, v126, v126
	v_fmac_f32_e32 v167, v128, v128
	v_fmac_f32_e32 v167, v129, v129
	v_fmac_f32_e32 v167, v122, v122
	v_fmac_f32_e32 v167, v123, v123
	v_fmac_f32_e32 v167, v124, v124
	v_fmac_f32_e32 v167, v125, v125
	v_fmac_f32_e32 v167, v118, v118
	v_fmac_f32_e32 v167, v119, v119
	v_fmac_f32_e32 v167, v120, v120
	v_fmac_f32_e32 v167, v121, v121
	v_fmac_f32_e32 v167, v114, v114
	v_fmac_f32_e32 v167, v115, v115
	v_fmac_f32_e32 v167, v116, v116
	s_waitcnt vmcnt(14)
	v_pk_mul_f32 v[140:141], v[130:131], v[130:131]
	v_fmac_f32_e32 v167, v117, v117
	v_add_f32_e32 v140, v167, v140
	v_pk_mul_f32 v[144:145], v[132:133], v[132:133]
	v_add_f32_e32 v140, v141, v140
	v_add_f32_e32 v140, v144, v140
	v_and_b32_e32 v146, 64, v166
	v_pk_mul_f32 v[156:157], v[134:135], v[134:135]
	v_add_f32_e32 v140, v145, v140
	v_xor_b32_e32 v143, 16, v166
	v_add_u32_e32 v168, 64, v146
	v_add_f32_e32 v140, v156, v140
	v_pk_mul_f32 v[158:159], v[136:137], v[136:137]
	v_cmp_lt_i32_e32 vcc, v143, v168
	v_add_f32_e32 v140, v157, v140
	v_add_f32_e32 v140, v158, v140
	v_cndmask_b32_e32 v143, v166, v143, vcc
	v_lshlrev_b32_e32 v146, 2, v143
	v_add_f32_e32 v140, v159, v140
	ds_bpermute_b32 v141, v146, v140
	v_xor_b32_e32 v148, 32, v166
	v_cmp_lt_i32_e32 vcc, v148, v168
	v_lshrrev_b32_e32 v151, 6, v150
	s_lshl_b32 s2, s58, 2
	v_cndmask_b32_e32 v144, v166, v148, vcc
	v_lshlrev_b32_e32 v148, 2, v144
	s_waitcnt lgkmcnt(0)
	v_add_f32_e32 v141, v140, v141
	ds_bpermute_b32 v156, v148, v141
	v_mov_b64_e32 v[160:161], s[24:25]
	v_and_or_b32 v140, v151, 3, s2
	v_mad_i64_i32 v[144:145], s[2:3], v139, s57, v[160:161]
	s_waitcnt lgkmcnt(0)
	v_add_f32_e32 v139, v141, v156
	v_fmamk_f32 v139, v139, 0x3c2aaaab, v1
	v_mul_f32_e32 v141, 0x4b800000, v139
	v_cmp_gt_f32_e32 vcc, s56, v139
	v_mul_lo_u32 v140, v140, s55
	v_mov_b32_e32 v143, v163
	v_cndmask_b32_e32 v139, v139, v141, vcc
	v_rsq_f32_e32 v139, v139
	v_ashrrev_i32_e32 v141, 31, v140
	v_lshl_add_u64 v[144:145], v[140:141], 1, v[144:145]
	v_lshl_add_u64 v[156:157], v[144:145], 0, v[142:143]
	v_mul_f32_e32 v143, 0x45800000, v139
	v_cndmask_b32_e32 v158, v139, v143, vcc
	v_mul_f32_e32 v126, v126, v158
	v_mul_f32_e32 v127, v127, v158
	v_mul_f32_e32 v128, v128, v158
	v_mul_f32_e32 v129, v129, v158
	v_mul_f32_e32 v122, v122, v158
	v_mul_f32_e32 v123, v123, v158
	v_mul_f32_e32 v124, v124, v158
	v_mul_f32_e32 v125, v125, v158
	v_mul_f32_e32 v118, v118, v158
	v_mul_f32_e32 v119, v119, v158
	v_mul_f32_e32 v120, v120, v158
	v_mul_f32_e32 v121, v121, v158
	v_mul_f32_e32 v114, v114, v158
	v_mul_f32_e32 v115, v115, v158
	v_mul_f32_e32 v116, v116, v158
	v_mul_f32_e32 v117, v117, v158
	s_cmp_eq_u32 s62, 1
	v_cmp_gt_u32_e64 s[4:5], 2, v149
	s_cselect_b64 s[30:31], -1, 0
	v_mul_f32_e32 v126, v170, v126
	v_mul_f32_e32 v127, v171, v127
	v_mul_f32_e32 v128, v172, v128
	v_mul_f32_e32 v129, v173, v129
	v_cvt_pk_bf16_f32 v126, v126, v127
	v_cvt_pk_bf16_f32 v127, v128, v129
	global_store_dwordx2 v[156:157], v[126:127], off
	s_cmp_lg_u32 s62, 1
	v_mul_f32_e32 v122, v174, v122
	v_mul_f32_e32 v123, v175, v123
	v_mul_f32_e32 v124, v176, v124
	v_mul_f32_e32 v125, v177, v125
	v_cvt_pk_bf16_f32 v122, v122, v123
	v_cvt_pk_bf16_f32 v123, v124, v125
	global_store_dwordx2 v[156:157], v[122:123], off offset:32
	v_mul_f32_e32 v118, v178, v118
	v_mul_f32_e32 v119, v179, v119
	v_mul_f32_e32 v120, v180, v120
	v_mul_f32_e32 v121, v121, v181
	v_cvt_pk_bf16_f32 v118, v118, v119
	v_cvt_pk_bf16_f32 v119, v120, v121
	global_store_dwordx2 v[156:157], v[118:119], off offset:64
	v_and_b32_e32 v122, 16, v150
	v_cmp_eq_u32_e64 s[2:3], 0, v122
	v_mul_f32_e32 v114, v114, v182
	v_mul_f32_e32 v115, v115, v183
	v_mul_f32_e32 v116, v116, v184
	v_mul_f32_e32 v117, v117, v185
	v_cvt_pk_bf16_f32 v114, v114, v115
	v_cvt_pk_bf16_f32 v115, v116, v117
	global_store_dwordx2 v[156:157], v[114:115], off offset:96
	s_nop 0
	v_mov_b32_e32 v114, v186
	v_mov_b32_e32 v115, v187
	v_mov_b32_e32 v116, v188
	v_mov_b32_e32 v117, v189
	v_pk_mul_f32 v[114:115], v[158:159], v[114:115] op_sel_hi:[0,1]
	v_pk_mul_f32 v[116:117], v[158:159], v[116:117] op_sel_hi:[0,1]
	v_pk_mul_f32 v[122:123], v[158:159], v[190:191] op_sel_hi:[0,1]
	v_pk_mul_f32 v[124:125], v[158:159], v[192:193] op_sel_hi:[0,1]
	v_pk_mul_f32 v[120:121], v[130:131], v[114:115]
	v_pk_mul_f32 v[118:119], v[132:133], v[116:117]
	v_pk_mul_f32 v[116:117], v[134:135], v[122:123]
	v_pk_mul_f32 v[114:115], v[136:137], v[124:125]
	s_cbranch_scc1 .LBB0_626
	v_add_u32_e32 v122, s60, v147
	v_ashrrev_i32_e32 v123, 6, v122
	v_and_b32_e32 v122, 63, v122
	v_cndmask_b32_e64 v122, v122, v123, s[4:5]
	v_cvt_f32_i32_e32 v130, v122
	ds_bpermute_b32 v122, v146, v120
	ds_bpermute_b32 v123, v146, v121
	v_mul_f32_e32 v125, 0x3ea1e89b, v130
	v_mul_f32_e32 v126, 0.15915494, v130
	v_mul_f32_e32 v127, 0.15915494, v125
	v_sin_f32_e32 v124, v126
	v_sin_f32_e32 v125, v127
	v_mul_f32_e32 v129, 0x3d0186e3, v130
	v_mul_f32_e32 v132, 0.15915494, v129
	v_cos_f32_e32 v126, v126
	s_waitcnt lgkmcnt(0)
	v_pk_mul_f32 v[122:123], v[124:125], v[122:123]
	v_mul_f32_e32 v125, 0x3dcccccd, v130
	ds_bpermute_b32 v124, v146, v118
	v_mul_f32_e32 v131, 0.15915494, v125
	ds_bpermute_b32 v125, v146, v119
	v_cos_f32_e32 v127, v127
	v_sin_f32_e32 v128, v131
	v_sin_f32_e32 v129, v132
	v_cndmask_b32_e64 v123, v123, -v123, s[2:3]
	v_cndmask_b32_e64 v122, v122, -v122, s[2:3]
	v_pk_fma_f32 v[120:121], v[126:127], v[120:121], v[122:123]
	s_waitcnt lgkmcnt(0)
	v_pk_mul_f32 v[124:125], v[128:129], v[124:125]
	v_mul_f32_e32 v127, 0x3c23d70b, v130
	v_mul_f32_e32 v129, 0x3b4f3e39, v130
	v_cos_f32_e32 v122, v131
	v_cos_f32_e32 v123, v132
	ds_bpermute_b32 v126, v146, v116
	v_mul_f32_e32 v131, 0.15915494, v127
	ds_bpermute_b32 v127, v146, v117
	v_mul_f32_e32 v132, 0.15915494, v129
	v_sin_f32_e32 v128, v131
	v_sin_f32_e32 v129, v132
	v_cndmask_b32_e64 v125, v125, -v125, s[2:3]
	v_cndmask_b32_e64 v124, v124, -v124, s[2:3]
	v_pk_fma_f32 v[118:119], v[122:123], v[118:119], v[124:125]
	v_cos_f32_e32 v122, v131
	v_cos_f32_e32 v123, v132
	s_waitcnt lgkmcnt(0)
	v_pk_mul_f32 v[124:125], v[128:129], v[126:127]
	v_mul_f32_e32 v127, 0x3a831270, v130
	v_mul_f32_e32 v129, 0x39a5cb61, v130
	ds_bpermute_b32 v126, v146, v114
	v_mul_f32_e32 v131, 0.15915494, v127
	ds_bpermute_b32 v127, v146, v115
	v_mul_f32_e32 v130, 0.15915494, v129
	v_sin_f32_e32 v128, v131
	v_sin_f32_e32 v129, v130
	v_cndmask_b32_e64 v125, v125, -v125, s[2:3]
	v_cndmask_b32_e64 v124, v124, -v124, s[2:3]
	v_pk_fma_f32 v[116:117], v[122:123], v[116:117], v[124:125]
	v_cos_f32_e32 v122, v131
	v_cos_f32_e32 v123, v130
	s_waitcnt lgkmcnt(0)
	v_pk_mul_f32 v[124:125], v[128:129], v[126:127]
	s_nop 0
	v_cndmask_b32_e64 v125, v125, -v125, s[2:3]
	v_cndmask_b32_e64 v124, v124, -v124, s[2:3]
	v_pk_fma_f32 v[114:115], v[122:123], v[114:115], v[124:125]
.LBB0_626:
	v_lshl_add_u64 v[124:125], s[20:21], 0, v[162:163]
	v_lshlrev_b32_e32 v162, 1, v142
	v_cvt_pk_bf16_f32 v131, v114, v115
	v_lshl_add_u64 v[114:115], v[144:145], 0, v[162:163]
	v_cvt_pk_bf16_f32 v128, v120, v121
	v_cvt_pk_bf16_f32 v129, v118, v119
	v_cvt_pk_bf16_f32 v130, v116, v117
	global_store_dwordx4 v[114:115], v[128:131], off offset:128
	v_mov_b32_e32 v139, v163
	v_lshlrev_b32_e32 v126, 2, v149
	v_lshl_add_u64 v[122:123], s[20:21], 0, v[138:139]
	v_or_b32_e32 v130, 16, v147
	s_cmp_gt_i32 s62, 1
	s_mov_b64 s[6:7], -1
	s_cbranch_scc0 .LBB0_628
	v_add_u32_e32 v114, s64, v130
	v_ashrrev_i32_e32 v115, 31, v114
	v_lshlrev_b64 v[114:115], 7, v[114:115]
	v_lshl_add_u64 v[114:115], s[22:23], 0, v[114:115]
	v_mov_b32_e32 v139, v163
	v_lshl_add_u64 v[114:115], v[114:115], 0, v[138:139]
	s_waitcnt vmcnt(17)
	v_mov_b32_e32 v118, v198
	v_mov_b32_e32 v119, v199
	v_mov_b32_e32 v120, v200
	v_mov_b32_e32 v121, v201
	s_nop 0
	v_mov_b32_e32 v114, v152
	v_mov_b32_e32 v115, v153
	v_mov_b32_e32 v116, v154
	v_mov_b32_e32 v117, v155
	s_mov_b64 s[6:7], 0
.LBB0_628:
	s_andn2_b64 vcc, exec, s[6:7]
	v_add_u32_e32 v128, s61, v130
	s_cbranch_vccnz .LBB0_632
	s_cmp_lg_u32 s62, 0
	v_mov_b32_e32 v114, v128
	s_cbranch_scc0 .LBB0_631
	v_add_u32_e32 v114, s63, v130
.LBB0_631:
	v_mov_b64_e32 v[116:117], s[14:15]
	v_mad_i64_i32 v[114:115], s[6:7], v114, s54, v[116:117]
	v_lshl_add_u64 v[114:115], v[114:115], 0, v[162:163]
	s_waitcnt vmcnt(11)
	v_mov_b32_e32 v118, v198
	v_mov_b32_e32 v119, v199
	v_mov_b32_e32 v120, v200
	v_mov_b32_e32 v121, v201
	v_lshlrev_b32_e32 v114, 16, v118
	v_and_b32_e32 v115, 0xffff0000, v118
	v_lshlrev_b32_e32 v116, 16, v119
	v_and_b32_e32 v117, 0xffff0000, v119
	v_lshlrev_b32_e32 v118, 16, v120
	v_and_b32_e32 v119, 0xffff0000, v120
	v_lshlrev_b32_e32 v120, 16, v121
	v_and_b32_e32 v121, 0xffff0000, v121
.LBB0_632:
	v_mul_f32_e32 v127, v111, v111
	v_fmac_f32_e32 v127, v110, v110
	v_fmac_f32_e32 v127, v112, v112
	v_fmac_f32_e32 v127, v113, v113
	v_fmac_f32_e32 v127, v106, v106
	v_fmac_f32_e32 v127, v107, v107
	v_fmac_f32_e32 v127, v108, v108
	v_fmac_f32_e32 v127, v109, v109
	v_fmac_f32_e32 v127, v102, v102
	v_fmac_f32_e32 v127, v103, v103
	v_fmac_f32_e32 v127, v104, v104
	v_fmac_f32_e32 v127, v105, v105
	v_fmac_f32_e32 v127, v98, v98
	v_fmac_f32_e32 v127, v99, v99
	v_fmac_f32_e32 v127, v100, v100
	v_pk_mul_f32 v[136:137], v[114:115], v[114:115]
	v_fmac_f32_e32 v127, v101, v101
	v_add_f32_e32 v127, v127, v136
	v_pk_mul_f32 v[142:143], v[116:117], v[116:117]
	v_add_f32_e32 v127, v137, v127
	v_add_f32_e32 v127, v142, v127
	v_pk_mul_f32 v[144:145], v[118:119], v[118:119]
	v_add_f32_e32 v127, v143, v127
	v_add_f32_e32 v127, v144, v127
	v_pk_mul_f32 v[150:151], v[120:121], v[120:121]
	v_add_f32_e32 v127, v145, v127
	v_add_f32_e32 v127, v150, v127
	v_add_f32_e32 v127, v151, v127
	ds_bpermute_b32 v129, v146, v127
	v_mov_b64_e32 v[136:137], s[24:25]
	v_lshlrev_b32_e32 v126, 1, v126
	s_waitcnt lgkmcnt(0)
	v_add_f32_e32 v129, v127, v129
	ds_bpermute_b32 v131, v148, v129
	v_mov_b32_e32 v127, v163
	s_waitcnt lgkmcnt(0)
	v_add_f32_e32 v129, v129, v131
	v_fmamk_f32 v129, v129, 0x3c2aaaab, v1
	v_mul_f32_e32 v131, 0x4b800000, v129
	v_cmp_gt_f32_e32 vcc, s56, v129
	s_nop 1
	v_cndmask_b32_e32 v129, v129, v131, vcc
	v_rsq_f32_e32 v131, v129
	v_mad_i64_i32 v[128:129], s[6:7], v128, s57, v[136:137]
	v_lshl_add_u64 v[128:129], v[140:141], 1, v[128:129]
	v_lshl_add_u64 v[136:137], v[128:129], 0, v[126:127]
	v_mul_f32_e32 v127, 0x45800000, v131
	v_cndmask_b32_e32 v142, v131, v127, vcc
	v_mul_f32_e32 v110, v110, v142
	v_mul_f32_e32 v111, v111, v142
	v_mul_f32_e32 v112, v112, v142
	v_mul_f32_e32 v113, v113, v142
	v_mul_f32_e32 v106, v106, v142
	v_mul_f32_e32 v107, v107, v142
	v_mul_f32_e32 v108, v108, v142
	v_mul_f32_e32 v109, v109, v142
	v_mul_f32_e32 v102, v102, v142
	v_mul_f32_e32 v103, v103, v142
	v_mul_f32_e32 v104, v104, v142
	v_mul_f32_e32 v105, v105, v142
	v_mul_f32_e32 v98, v98, v142
	v_mul_f32_e32 v99, v99, v142
	v_mul_f32_e32 v100, v100, v142
	v_mul_f32_e32 v101, v101, v142
	s_andn2_b64 vcc, exec, s[30:31]
	v_mul_f32_e32 v110, v170, v110
	v_mul_f32_e32 v111, v171, v111
	v_mul_f32_e32 v112, v172, v112
	v_mul_f32_e32 v113, v173, v113
	v_cvt_pk_bf16_f32 v110, v110, v111
	v_cvt_pk_bf16_f32 v111, v112, v113
	global_store_dwordx2 v[136:137], v[110:111], off
	v_mul_f32_e32 v106, v174, v106
	v_mul_f32_e32 v107, v175, v107
	v_mul_f32_e32 v108, v176, v108
	v_mul_f32_e32 v109, v177, v109
	v_cvt_pk_bf16_f32 v106, v106, v107
	v_cvt_pk_bf16_f32 v107, v108, v109
	global_store_dwordx2 v[136:137], v[106:107], off offset:32
	v_mul_f32_e32 v102, v178, v102
	v_mul_f32_e32 v103, v179, v103
	v_mul_f32_e32 v104, v180, v104
	v_mul_f32_e32 v105, v105, v181
	v_cvt_pk_bf16_f32 v102, v102, v103
	v_cvt_pk_bf16_f32 v103, v104, v105
	global_store_dwordx2 v[136:137], v[102:103], off offset:64
	v_cndmask_b32_e64 v106, 0, 1, s[30:31]
	v_cmp_ne_u32_e64 s[6:7], 1, v106
	v_mul_f32_e32 v98, v98, v182
	v_mul_f32_e32 v99, v99, v183
	v_mul_f32_e32 v100, v100, v184
	v_mul_f32_e32 v101, v101, v185
	v_cvt_pk_bf16_f32 v98, v98, v99
	v_cvt_pk_bf16_f32 v99, v100, v101
	global_store_dwordx2 v[136:137], v[98:99], off offset:96
	s_nop 0
	v_mov_b32_e32 v98, v186
	v_mov_b32_e32 v99, v187
	v_mov_b32_e32 v100, v188
	v_mov_b32_e32 v101, v189
	v_pk_mul_f32 v[98:99], v[142:143], v[98:99] op_sel_hi:[0,1]
	v_pk_mul_f32 v[100:101], v[142:143], v[100:101] op_sel_hi:[0,1]
	v_pk_mul_f32 v[106:107], v[142:143], v[190:191] op_sel_hi:[0,1]
	v_pk_mul_f32 v[108:109], v[142:143], v[192:193] op_sel_hi:[0,1]
	v_pk_mul_f32 v[104:105], v[114:115], v[98:99]
	v_pk_mul_f32 v[102:103], v[116:117], v[100:101]
	v_pk_mul_f32 v[100:101], v[118:119], v[106:107]
	v_pk_mul_f32 v[98:99], v[120:121], v[108:109]
	s_cbranch_vccnz .LBB0_634
	v_add_u32_e32 v106, s60, v130
	v_ashrrev_i32_e32 v107, 6, v106
	v_and_b32_e32 v106, 63, v106
	v_cndmask_b32_e64 v106, v106, v107, s[4:5]
	v_cvt_f32_i32_e32 v114, v106
	ds_bpermute_b32 v106, v146, v104
	ds_bpermute_b32 v107, v146, v105
	v_mul_f32_e32 v109, 0x3ea1e89b, v114
	v_mul_f32_e32 v110, 0.15915494, v114
	v_mul_f32_e32 v111, 0.15915494, v109
	v_sin_f32_e32 v108, v110
	v_sin_f32_e32 v109, v111
	v_mul_f32_e32 v113, 0x3d0186e3, v114
	v_mul_f32_e32 v116, 0.15915494, v113
	v_cos_f32_e32 v110, v110
	s_waitcnt lgkmcnt(0)
	v_pk_mul_f32 v[106:107], v[108:109], v[106:107]
	v_mul_f32_e32 v109, 0x3dcccccd, v114
	ds_bpermute_b32 v108, v146, v102
	v_mul_f32_e32 v115, 0.15915494, v109
	ds_bpermute_b32 v109, v146, v103
	v_cos_f32_e32 v111, v111
	v_sin_f32_e32 v112, v115
	v_sin_f32_e32 v113, v116
	v_cndmask_b32_e64 v107, v107, -v107, s[2:3]
	v_cndmask_b32_e64 v106, v106, -v106, s[2:3]
	v_pk_fma_f32 v[104:105], v[110:111], v[104:105], v[106:107]
	s_waitcnt lgkmcnt(0)
	v_pk_mul_f32 v[108:109], v[112:113], v[108:109]
	v_mul_f32_e32 v111, 0x3c23d70b, v114
	v_mul_f32_e32 v113, 0x3b4f3e39, v114
	v_cos_f32_e32 v106, v115
	v_cos_f32_e32 v107, v116
	ds_bpermute_b32 v110, v146, v100
	v_mul_f32_e32 v115, 0.15915494, v111
	ds_bpermute_b32 v111, v146, v101
	v_mul_f32_e32 v116, 0.15915494, v113
	v_sin_f32_e32 v112, v115
	v_sin_f32_e32 v113, v116
	v_cndmask_b32_e64 v109, v109, -v109, s[2:3]
	v_cndmask_b32_e64 v108, v108, -v108, s[2:3]
	v_pk_fma_f32 v[102:103], v[106:107], v[102:103], v[108:109]
	v_cos_f32_e32 v106, v115
	v_cos_f32_e32 v107, v116
	s_waitcnt lgkmcnt(0)
	v_pk_mul_f32 v[108:109], v[112:113], v[110:111]
	v_mul_f32_e32 v111, 0x3a831270, v114
	v_mul_f32_e32 v113, 0x39a5cb61, v114
	ds_bpermute_b32 v110, v146, v98
	v_mul_f32_e32 v115, 0.15915494, v111
	ds_bpermute_b32 v111, v146, v99
	v_mul_f32_e32 v114, 0.15915494, v113
	v_sin_f32_e32 v112, v115
	v_sin_f32_e32 v113, v114
	v_cndmask_b32_e64 v109, v109, -v109, s[2:3]
	v_cndmask_b32_e64 v108, v108, -v108, s[2:3]
	v_pk_fma_f32 v[100:101], v[106:107], v[100:101], v[108:109]
	v_cos_f32_e32 v106, v115
	v_cos_f32_e32 v107, v114
	s_waitcnt lgkmcnt(0)
	v_pk_mul_f32 v[108:109], v[112:113], v[110:111]
	s_nop 0
	v_cndmask_b32_e64 v109, v109, -v109, s[2:3]
	v_cndmask_b32_e64 v108, v108, -v108, s[2:3]
	v_pk_fma_f32 v[98:99], v[106:107], v[98:99], v[108:109]
.LBB0_634:
	s_nop 0
	v_cvt_pk_bf16_f32 v107, v98, v99
	v_lshl_add_u64 v[98:99], v[128:129], 0, v[162:163]
	v_cvt_pk_bf16_f32 v104, v104, v105
	v_cvt_pk_bf16_f32 v105, v102, v103
	v_cvt_pk_bf16_f32 v106, v100, v101
	global_store_dwordx4 v[98:99], v[104:107], off offset:128
	v_or_b32_e32 v108, 32, v147
	s_cmp_gt_i32 s62, 1
	s_mov_b64 s[30:31], -1
	s_cbranch_scc0 .LBB0_636
	v_add_u32_e32 v98, s64, v108
	v_ashrrev_i32_e32 v99, 31, v98
	v_lshlrev_b64 v[98:99], 7, v[98:99]
	v_lshl_add_u64 v[98:99], s[22:23], 0, v[98:99]
	v_mov_b32_e32 v139, v163
	v_lshl_add_u64 v[98:99], v[98:99], 0, v[138:139]
	s_waitcnt vmcnt(20)
	v_mov_b32_e32 v102, v206
	v_mov_b32_e32 v103, v207
	v_mov_b32_e32 v104, v208
	v_mov_b32_e32 v105, v209
	s_nop 0
	v_mov_b32_e32 v98, v202
	v_mov_b32_e32 v99, v203
	v_mov_b32_e32 v100, v204
	v_mov_b32_e32 v101, v205
	s_mov_b64 s[30:31], 0
.LBB0_636:
	s_andn2_b64 vcc, exec, s[30:31]
	v_add_u32_e32 v106, s61, v108
	s_cbranch_vccnz .LBB0_640
	s_cmp_lg_u32 s62, 0
	v_mov_b32_e32 v98, v106
	s_cbranch_scc0 .LBB0_639
	v_add_u32_e32 v98, s63, v108
.LBB0_639:
	v_mov_b64_e32 v[100:101], s[14:15]
	v_mad_i64_i32 v[98:99], s[30:31], v98, s54, v[100:101]
	v_lshl_add_u64 v[98:99], v[98:99], 0, v[162:163]
	s_waitcnt vmcnt(15)
	v_mov_b32_e32 v102, v206
	v_mov_b32_e32 v103, v207
	v_mov_b32_e32 v104, v208
	v_mov_b32_e32 v105, v209
	v_lshlrev_b32_e32 v98, 16, v102
	v_and_b32_e32 v99, 0xffff0000, v102
	v_lshlrev_b32_e32 v100, 16, v103
	v_and_b32_e32 v101, 0xffff0000, v103
	v_lshlrev_b32_e32 v102, 16, v104
	v_and_b32_e32 v103, 0xffff0000, v104
	v_lshlrev_b32_e32 v104, 16, v105
	v_and_b32_e32 v105, 0xffff0000, v105
.LBB0_640:
	v_mul_f32_e32 v107, v95, v95
	v_fmac_f32_e32 v107, v94, v94
	v_fmac_f32_e32 v107, v96, v96
	v_fmac_f32_e32 v107, v97, v97
	v_fmac_f32_e32 v107, v90, v90
	v_fmac_f32_e32 v107, v91, v91
	v_fmac_f32_e32 v107, v92, v92
	v_fmac_f32_e32 v107, v93, v93
	v_fmac_f32_e32 v107, v86, v86
	v_fmac_f32_e32 v107, v87, v87
	v_fmac_f32_e32 v107, v88, v88
	v_fmac_f32_e32 v107, v89, v89
	v_fmac_f32_e32 v107, v82, v82
	v_fmac_f32_e32 v107, v83, v83
	v_fmac_f32_e32 v107, v84, v84
	v_pk_mul_f32 v[114:115], v[98:99], v[98:99]
	v_fmac_f32_e32 v107, v85, v85
	v_add_f32_e32 v107, v107, v114
	v_pk_mul_f32 v[116:117], v[100:101], v[100:101]
	v_add_f32_e32 v107, v115, v107
	v_add_f32_e32 v107, v116, v107
	v_pk_mul_f32 v[118:119], v[102:103], v[102:103]
	v_add_f32_e32 v107, v117, v107
	v_add_f32_e32 v107, v118, v107
	v_pk_mul_f32 v[120:121], v[104:105], v[104:105]
	v_add_f32_e32 v107, v119, v107
	v_add_f32_e32 v107, v120, v107
	v_add_f32_e32 v107, v121, v107
	ds_bpermute_b32 v109, v146, v107
	v_mov_b64_e32 v[114:115], s[24:25]
	v_mov_b32_e32 v127, v163
	s_waitcnt lgkmcnt(0)
	v_add_f32_e32 v107, v107, v109
	ds_bpermute_b32 v109, v148, v107
	s_waitcnt lgkmcnt(0)
	v_add_f32_e32 v107, v107, v109
	v_fmamk_f32 v107, v107, 0x3c2aaaab, v1
	v_mul_f32_e32 v109, 0x4b800000, v107
	v_cmp_gt_f32_e32 vcc, s56, v107
	s_nop 1
	v_cndmask_b32_e32 v107, v107, v109, vcc
	v_rsq_f32_e32 v109, v107
	v_mad_i64_i32 v[106:107], s[30:31], v106, s57, v[114:115]
	v_lshl_add_u64 v[106:107], v[140:141], 1, v[106:107]
	v_mul_f32_e32 v116, 0x45800000, v109
	v_cndmask_b32_e32 v116, v109, v116, vcc
	v_mul_f32_e32 v94, v94, v116
	v_mul_f32_e32 v95, v95, v116
	v_lshl_add_u64 v[114:115], v[106:107], 0, v[126:127]
	v_mul_f32_e32 v96, v96, v116
	v_mul_f32_e32 v97, v97, v116
	v_mul_f32_e32 v90, v90, v116
	v_mul_f32_e32 v91, v91, v116
	v_mul_f32_e32 v92, v92, v116
	v_mul_f32_e32 v93, v93, v116
	v_mul_f32_e32 v86, v86, v116
	v_mul_f32_e32 v87, v87, v116
	v_mul_f32_e32 v88, v88, v116
	v_mul_f32_e32 v89, v89, v116
	v_mul_f32_e32 v82, v82, v116
	v_mul_f32_e32 v83, v83, v116
	v_mul_f32_e32 v84, v84, v116
	v_mul_f32_e32 v85, v85, v116
	s_and_b64 vcc, exec, s[6:7]
	v_mul_f32_e32 v94, v170, v94
	v_mul_f32_e32 v95, v171, v95
	v_mul_f32_e32 v96, v172, v96
	v_mul_f32_e32 v97, v173, v97
	v_cvt_pk_bf16_f32 v94, v94, v95
	v_cvt_pk_bf16_f32 v95, v96, v97
	global_store_dwordx2 v[114:115], v[94:95], off
	v_mul_f32_e32 v90, v174, v90
	v_mul_f32_e32 v91, v175, v91
	v_mul_f32_e32 v92, v176, v92
	v_mul_f32_e32 v93, v177, v93
	v_cvt_pk_bf16_f32 v90, v90, v91
	v_cvt_pk_bf16_f32 v91, v92, v93
	global_store_dwordx2 v[114:115], v[90:91], off offset:32
	v_mul_f32_e32 v86, v178, v86
	v_mul_f32_e32 v87, v179, v87
	v_mul_f32_e32 v88, v180, v88
	v_mul_f32_e32 v89, v89, v181
	v_cvt_pk_bf16_f32 v86, v86, v87
	v_cvt_pk_bf16_f32 v87, v88, v89
	global_store_dwordx2 v[114:115], v[86:87], off offset:64
	v_mul_f32_e32 v82, v82, v182
	v_mul_f32_e32 v83, v83, v183
	v_mul_f32_e32 v84, v84, v184
	v_mul_f32_e32 v85, v85, v185
	v_cvt_pk_bf16_f32 v82, v82, v83
	v_cvt_pk_bf16_f32 v83, v84, v85
	global_store_dwordx2 v[114:115], v[82:83], off offset:96
	s_nop 0
	v_mov_b32_e32 v82, v186
	v_mov_b32_e32 v83, v187
	v_mov_b32_e32 v84, v188
	v_mov_b32_e32 v85, v189
	v_pk_mul_f32 v[82:83], v[116:117], v[82:83] op_sel_hi:[0,1]
	v_pk_mul_f32 v[84:85], v[116:117], v[84:85] op_sel_hi:[0,1]
	v_pk_mul_f32 v[90:91], v[116:117], v[190:191] op_sel_hi:[0,1]
	v_pk_mul_f32 v[92:93], v[116:117], v[192:193] op_sel_hi:[0,1]
	v_pk_mul_f32 v[88:89], v[98:99], v[82:83]
	v_pk_mul_f32 v[86:87], v[100:101], v[84:85]
	v_pk_mul_f32 v[84:85], v[102:103], v[90:91]
	v_pk_mul_f32 v[82:83], v[104:105], v[92:93]
	s_cbranch_vccnz .LBB0_642
	v_add_u32_e32 v90, s60, v108
	v_ashrrev_i32_e32 v91, 6, v90
	v_and_b32_e32 v90, 63, v90
	v_cndmask_b32_e64 v90, v90, v91, s[4:5]
	v_cvt_f32_i32_e32 v98, v90
	ds_bpermute_b32 v90, v146, v88
	ds_bpermute_b32 v91, v146, v89
	v_mul_f32_e32 v93, 0x3ea1e89b, v98
	v_mul_f32_e32 v94, 0.15915494, v98
	v_mul_f32_e32 v95, 0.15915494, v93
	v_sin_f32_e32 v92, v94
	v_sin_f32_e32 v93, v95
	v_mul_f32_e32 v97, 0x3d0186e3, v98
	v_mul_f32_e32 v100, 0.15915494, v97
	v_cos_f32_e32 v94, v94
	s_waitcnt lgkmcnt(0)
	v_pk_mul_f32 v[90:91], v[92:93], v[90:91]
	v_mul_f32_e32 v93, 0x3dcccccd, v98
	ds_bpermute_b32 v92, v146, v86
	v_mul_f32_e32 v99, 0.15915494, v93
	ds_bpermute_b32 v93, v146, v87
	v_cos_f32_e32 v95, v95
	v_sin_f32_e32 v96, v99
	v_sin_f32_e32 v97, v100
	v_cndmask_b32_e64 v91, v91, -v91, s[2:3]
	v_cndmask_b32_e64 v90, v90, -v90, s[2:3]
	v_pk_fma_f32 v[88:89], v[94:95], v[88:89], v[90:91]
	s_waitcnt lgkmcnt(0)
	v_pk_mul_f32 v[92:93], v[96:97], v[92:93]
	v_mul_f32_e32 v95, 0x3c23d70b, v98
	v_mul_f32_e32 v97, 0x3b4f3e39, v98
	v_cos_f32_e32 v90, v99
	v_cos_f32_e32 v91, v100
	ds_bpermute_b32 v94, v146, v84
	v_mul_f32_e32 v99, 0.15915494, v95
	ds_bpermute_b32 v95, v146, v85
	v_mul_f32_e32 v100, 0.15915494, v97
	v_sin_f32_e32 v96, v99
	v_sin_f32_e32 v97, v100
	v_cndmask_b32_e64 v93, v93, -v93, s[2:3]
	v_cndmask_b32_e64 v92, v92, -v92, s[2:3]
	v_pk_fma_f32 v[86:87], v[90:91], v[86:87], v[92:93]
	v_cos_f32_e32 v90, v99
	v_cos_f32_e32 v91, v100
	s_waitcnt lgkmcnt(0)
	v_pk_mul_f32 v[92:93], v[96:97], v[94:95]
	v_mul_f32_e32 v95, 0x3a831270, v98
	v_mul_f32_e32 v97, 0x39a5cb61, v98
	ds_bpermute_b32 v94, v146, v82
	v_mul_f32_e32 v99, 0.15915494, v95
	ds_bpermute_b32 v95, v146, v83
	v_mul_f32_e32 v98, 0.15915494, v97
	v_sin_f32_e32 v96, v99
	v_sin_f32_e32 v97, v98
	v_cndmask_b32_e64 v93, v93, -v93, s[2:3]
	v_cndmask_b32_e64 v92, v92, -v92, s[2:3]
	v_pk_fma_f32 v[84:85], v[90:91], v[84:85], v[92:93]
	v_cos_f32_e32 v90, v99
	v_cos_f32_e32 v91, v98
	s_waitcnt lgkmcnt(0)
	v_pk_mul_f32 v[92:93], v[96:97], v[94:95]
	s_nop 0
	v_cndmask_b32_e64 v93, v93, -v93, s[2:3]
	v_cndmask_b32_e64 v92, v92, -v92, s[2:3]
	v_pk_fma_f32 v[82:83], v[90:91], v[82:83], v[92:93]
.LBB0_642:
	s_nop 0
	v_cvt_pk_bf16_f32 v91, v82, v83
	v_lshl_add_u64 v[82:83], v[106:107], 0, v[162:163]
	v_cvt_pk_bf16_f32 v88, v88, v89
	v_cvt_pk_bf16_f32 v89, v86, v87
	v_cvt_pk_bf16_f32 v90, v84, v85
	global_store_dwordx4 v[82:83], v[88:91], off offset:128
	v_or_b32_e32 v92, 48, v147
	s_cmp_gt_i32 s62, 1
	s_mov_b64 s[30:31], -1
	s_cbranch_scc0 .LBB0_644
	v_add_u32_e32 v82, s64, v92
	v_ashrrev_i32_e32 v83, 31, v82
	v_lshlrev_b64 v[82:83], 7, v[82:83]
	v_lshl_add_u64 v[82:83], s[22:23], 0, v[82:83]
	v_mov_b32_e32 v139, v163
	v_lshl_add_u64 v[82:83], v[82:83], 0, v[138:139]
	s_waitcnt vmcnt(23)
	v_mov_b32_e32 v86, v214
	v_mov_b32_e32 v87, v215
	v_mov_b32_e32 v88, v216
	v_mov_b32_e32 v89, v217
	s_nop 0
	v_mov_b32_e32 v82, v210
	v_mov_b32_e32 v83, v211
	v_mov_b32_e32 v84, v212
	v_mov_b32_e32 v85, v213
	s_mov_b64 s[30:31], 0
.LBB0_644:
	s_andn2_b64 vcc, exec, s[30:31]
	v_add_u32_e32 v90, s61, v92
	s_cbranch_vccnz .LBB0_648
	s_cmp_lg_u32 s62, 0
	v_mov_b32_e32 v82, v90
	s_cbranch_scc0 .LBB0_647
	v_add_u32_e32 v82, s63, v92
.LBB0_647:
	v_mov_b64_e32 v[84:85], s[14:15]
	v_mad_i64_i32 v[82:83], s[30:31], v82, s54, v[84:85]
	v_lshl_add_u64 v[82:83], v[82:83], 0, v[162:163]
	s_waitcnt vmcnt(19)
	v_mov_b32_e32 v86, v214
	v_mov_b32_e32 v87, v215
	v_mov_b32_e32 v88, v216
	v_mov_b32_e32 v89, v217
	v_lshlrev_b32_e32 v82, 16, v86
	v_and_b32_e32 v83, 0xffff0000, v86
	v_lshlrev_b32_e32 v84, 16, v87
	v_and_b32_e32 v85, 0xffff0000, v87
	v_lshlrev_b32_e32 v86, 16, v88
	v_and_b32_e32 v87, 0xffff0000, v88
	v_lshlrev_b32_e32 v88, 16, v89
	v_and_b32_e32 v89, 0xffff0000, v89
.LBB0_648:
	v_mul_f32_e32 v91, v79, v79
	v_fmac_f32_e32 v91, v78, v78
	v_fmac_f32_e32 v91, v80, v80
	v_fmac_f32_e32 v91, v81, v81
	v_fmac_f32_e32 v91, v74, v74
	v_fmac_f32_e32 v91, v75, v75
	v_fmac_f32_e32 v91, v76, v76
	v_fmac_f32_e32 v91, v77, v77
	v_fmac_f32_e32 v91, v70, v70
	v_fmac_f32_e32 v91, v71, v71
	v_fmac_f32_e32 v91, v72, v72
	v_fmac_f32_e32 v91, v73, v73
	v_fmac_f32_e32 v91, v66, v66
	v_fmac_f32_e32 v91, v67, v67
	v_fmac_f32_e32 v91, v68, v68
	v_pk_mul_f32 v[98:99], v[82:83], v[82:83]
	v_fmac_f32_e32 v91, v69, v69
	v_add_f32_e32 v91, v91, v98
	v_pk_mul_f32 v[100:101], v[84:85], v[84:85]
	v_add_f32_e32 v91, v99, v91
	v_add_f32_e32 v91, v100, v91
	v_pk_mul_f32 v[102:103], v[86:87], v[86:87]
	v_add_f32_e32 v91, v101, v91
	v_add_f32_e32 v91, v102, v91
	v_pk_mul_f32 v[104:105], v[88:89], v[88:89]
	v_add_f32_e32 v91, v103, v91
	v_add_f32_e32 v91, v104, v91
	v_add_f32_e32 v91, v105, v91
	ds_bpermute_b32 v93, v146, v91
	v_mov_b64_e32 v[98:99], s[24:25]
	v_mov_b32_e32 v127, v163
	s_waitcnt lgkmcnt(0)
	v_add_f32_e32 v91, v91, v93
	ds_bpermute_b32 v93, v148, v91
	s_waitcnt lgkmcnt(0)
	v_add_f32_e32 v91, v91, v93
	v_fmamk_f32 v91, v91, 0x3c2aaaab, v1
	v_mul_f32_e32 v93, 0x4b800000, v91
	v_cmp_gt_f32_e32 vcc, s56, v91
	s_nop 1
	v_cndmask_b32_e32 v91, v91, v93, vcc
	v_rsq_f32_e32 v93, v91
	v_mad_i64_i32 v[90:91], s[30:31], v90, s57, v[98:99]
	v_lshl_add_u64 v[90:91], v[140:141], 1, v[90:91]
	v_mul_f32_e32 v100, 0x45800000, v93
	v_cndmask_b32_e32 v100, v93, v100, vcc
	v_mul_f32_e32 v78, v78, v100
	v_mul_f32_e32 v79, v79, v100
	v_lshl_add_u64 v[98:99], v[90:91], 0, v[126:127]
	v_mul_f32_e32 v80, v80, v100
	v_mul_f32_e32 v81, v81, v100
	v_mul_f32_e32 v74, v74, v100
	v_mul_f32_e32 v75, v75, v100
	v_mul_f32_e32 v76, v76, v100
	v_mul_f32_e32 v77, v77, v100
	v_mul_f32_e32 v70, v70, v100
	v_mul_f32_e32 v71, v71, v100
	v_mul_f32_e32 v72, v72, v100
	v_mul_f32_e32 v73, v73, v100
	v_mul_f32_e32 v66, v66, v100
	v_mul_f32_e32 v67, v67, v100
	v_mul_f32_e32 v68, v68, v100
	v_mul_f32_e32 v69, v69, v100
	s_and_b64 vcc, exec, s[6:7]
	v_mul_f32_e32 v78, v170, v78
	v_mul_f32_e32 v79, v171, v79
	v_mul_f32_e32 v80, v172, v80
	v_mul_f32_e32 v81, v173, v81
	v_cvt_pk_bf16_f32 v78, v78, v79
	v_cvt_pk_bf16_f32 v79, v80, v81
	global_store_dwordx2 v[98:99], v[78:79], off
	v_mul_f32_e32 v74, v174, v74
	v_mul_f32_e32 v75, v175, v75
	v_mul_f32_e32 v76, v176, v76
	v_mul_f32_e32 v77, v177, v77
	v_cvt_pk_bf16_f32 v74, v74, v75
	v_cvt_pk_bf16_f32 v75, v76, v77
	global_store_dwordx2 v[98:99], v[74:75], off offset:32
	v_mul_f32_e32 v70, v178, v70
	v_mul_f32_e32 v71, v179, v71
	v_mul_f32_e32 v72, v180, v72
	v_mul_f32_e32 v73, v73, v181
	v_cvt_pk_bf16_f32 v70, v70, v71
	v_cvt_pk_bf16_f32 v71, v72, v73
	global_store_dwordx2 v[98:99], v[70:71], off offset:64
	v_mul_f32_e32 v66, v66, v182
	v_mul_f32_e32 v67, v67, v183
	v_mul_f32_e32 v68, v68, v184
	v_mul_f32_e32 v69, v69, v185
	v_cvt_pk_bf16_f32 v66, v66, v67
	v_cvt_pk_bf16_f32 v67, v68, v69
	global_store_dwordx2 v[98:99], v[66:67], off offset:96
	s_nop 0
	v_mov_b32_e32 v66, v186
	v_mov_b32_e32 v67, v187
	v_mov_b32_e32 v68, v188
	v_mov_b32_e32 v69, v189
	v_pk_mul_f32 v[66:67], v[100:101], v[66:67] op_sel_hi:[0,1]
	v_pk_mul_f32 v[68:69], v[100:101], v[68:69] op_sel_hi:[0,1]
	v_pk_mul_f32 v[74:75], v[100:101], v[190:191] op_sel_hi:[0,1]
	v_pk_mul_f32 v[76:77], v[100:101], v[192:193] op_sel_hi:[0,1]
	v_pk_mul_f32 v[72:73], v[82:83], v[66:67]
	v_pk_mul_f32 v[70:71], v[84:85], v[68:69]
	v_pk_mul_f32 v[68:69], v[86:87], v[74:75]
	v_pk_mul_f32 v[66:67], v[88:89], v[76:77]
	s_cbranch_vccnz .LBB0_650
	v_add_u32_e32 v74, s60, v92
	v_ashrrev_i32_e32 v75, 6, v74
	v_and_b32_e32 v74, 63, v74
	v_cndmask_b32_e64 v74, v74, v75, s[4:5]
	v_cvt_f32_i32_e32 v82, v74
	ds_bpermute_b32 v74, v146, v72
	ds_bpermute_b32 v75, v146, v73
	v_mul_f32_e32 v77, 0x3ea1e89b, v82
	v_mul_f32_e32 v78, 0.15915494, v82
	v_mul_f32_e32 v79, 0.15915494, v77
	v_sin_f32_e32 v76, v78
	v_sin_f32_e32 v77, v79
	v_mul_f32_e32 v81, 0x3d0186e3, v82
	v_mul_f32_e32 v84, 0.15915494, v81
	v_cos_f32_e32 v78, v78
	s_waitcnt lgkmcnt(0)
	v_pk_mul_f32 v[74:75], v[76:77], v[74:75]
	v_mul_f32_e32 v77, 0x3dcccccd, v82
	ds_bpermute_b32 v76, v146, v70
	v_mul_f32_e32 v83, 0.15915494, v77
	ds_bpermute_b32 v77, v146, v71
	v_cos_f32_e32 v79, v79
	v_sin_f32_e32 v80, v83
	v_sin_f32_e32 v81, v84
	v_cndmask_b32_e64 v75, v75, -v75, s[2:3]
	v_cndmask_b32_e64 v74, v74, -v74, s[2:3]
	v_pk_fma_f32 v[72:73], v[78:79], v[72:73], v[74:75]
	s_waitcnt lgkmcnt(0)
	v_pk_mul_f32 v[76:77], v[80:81], v[76:77]
	v_mul_f32_e32 v79, 0x3c23d70b, v82
	v_mul_f32_e32 v81, 0x3b4f3e39, v82
	v_cos_f32_e32 v74, v83
	v_cos_f32_e32 v75, v84
	ds_bpermute_b32 v78, v146, v68
	v_mul_f32_e32 v83, 0.15915494, v79
	ds_bpermute_b32 v79, v146, v69
	v_mul_f32_e32 v84, 0.15915494, v81
	v_sin_f32_e32 v80, v83
	v_sin_f32_e32 v81, v84
	v_cndmask_b32_e64 v77, v77, -v77, s[2:3]
	v_cndmask_b32_e64 v76, v76, -v76, s[2:3]
	v_pk_fma_f32 v[70:71], v[74:75], v[70:71], v[76:77]
	v_cos_f32_e32 v74, v83
	v_cos_f32_e32 v75, v84
	s_waitcnt lgkmcnt(0)
	v_pk_mul_f32 v[76:77], v[80:81], v[78:79]
	v_mul_f32_e32 v79, 0x3a831270, v82
	v_mul_f32_e32 v81, 0x39a5cb61, v82
	ds_bpermute_b32 v78, v146, v66
	v_mul_f32_e32 v83, 0.15915494, v79
	ds_bpermute_b32 v79, v146, v67
	v_mul_f32_e32 v82, 0.15915494, v81
	v_sin_f32_e32 v80, v83
	v_sin_f32_e32 v81, v82
	v_cndmask_b32_e64 v77, v77, -v77, s[2:3]
	v_cndmask_b32_e64 v76, v76, -v76, s[2:3]
	v_pk_fma_f32 v[68:69], v[74:75], v[68:69], v[76:77]
	v_cos_f32_e32 v74, v83
	v_cos_f32_e32 v75, v82
	s_waitcnt lgkmcnt(0)
	v_pk_mul_f32 v[76:77], v[80:81], v[78:79]
	s_nop 0
	v_cndmask_b32_e64 v77, v77, -v77, s[2:3]
	v_cndmask_b32_e64 v76, v76, -v76, s[2:3]
	v_pk_fma_f32 v[66:67], v[74:75], v[66:67], v[76:77]
.LBB0_650:
	s_nop 0
	v_cvt_pk_bf16_f32 v75, v66, v67
	v_lshl_add_u64 v[66:67], v[90:91], 0, v[162:163]
	v_cvt_pk_bf16_f32 v72, v72, v73
	v_cvt_pk_bf16_f32 v73, v70, v71
	v_cvt_pk_bf16_f32 v74, v68, v69
	global_store_dwordx4 v[66:67], v[72:75], off offset:128
	v_or_b32_e32 v76, 64, v147
	s_cmp_gt_i32 s62, 1
	s_mov_b64 s[30:31], -1
	s_cbranch_scc0 .LBB0_652
	v_add_u32_e32 v66, s64, v76
	v_ashrrev_i32_e32 v67, 31, v66
	v_lshlrev_b64 v[66:67], 7, v[66:67]
	v_lshl_add_u64 v[66:67], s[22:23], 0, v[66:67]
	v_mov_b32_e32 v139, v163
	v_lshl_add_u64 v[66:67], v[66:67], 0, v[138:139]
	s_waitcnt vmcnt(26)
	v_mov_b32_e32 v70, v226
	v_mov_b32_e32 v71, v227
	v_mov_b32_e32 v72, v228
	v_mov_b32_e32 v73, v229
	s_nop 0
	v_mov_b32_e32 v66, v218
	v_mov_b32_e32 v67, v219
	v_mov_b32_e32 v68, v220
	v_mov_b32_e32 v69, v221
	s_mov_b64 s[30:31], 0
.LBB0_652:
	s_andn2_b64 vcc, exec, s[30:31]
	v_add_u32_e32 v74, s61, v76
	s_cbranch_vccnz .LBB0_656
	s_cmp_lg_u32 s62, 0
	v_mov_b32_e32 v66, v74
	s_cbranch_scc0 .LBB0_655
	v_add_u32_e32 v66, s63, v76
.LBB0_655:
	v_mov_b64_e32 v[68:69], s[14:15]
	v_mad_i64_i32 v[66:67], s[30:31], v66, s54, v[68:69]
	v_lshl_add_u64 v[66:67], v[66:67], 0, v[162:163]
	s_waitcnt vmcnt(23)
	v_mov_b32_e32 v70, v226
	v_mov_b32_e32 v71, v227
	v_mov_b32_e32 v72, v228
	v_mov_b32_e32 v73, v229
	v_lshlrev_b32_e32 v66, 16, v70
	v_and_b32_e32 v67, 0xffff0000, v70
	v_lshlrev_b32_e32 v68, 16, v71
	v_and_b32_e32 v69, 0xffff0000, v71
	v_lshlrev_b32_e32 v70, 16, v72
	v_and_b32_e32 v71, 0xffff0000, v72
	v_lshlrev_b32_e32 v72, 16, v73
	v_and_b32_e32 v73, 0xffff0000, v73
.LBB0_656:
	v_mul_f32_e32 v75, v63, v63
	v_fmac_f32_e32 v75, v62, v62
	v_fmac_f32_e32 v75, v64, v64
	v_fmac_f32_e32 v75, v65, v65
	v_fmac_f32_e32 v75, v58, v58
	v_fmac_f32_e32 v75, v59, v59
	v_fmac_f32_e32 v75, v60, v60
	v_fmac_f32_e32 v75, v61, v61
	v_fmac_f32_e32 v75, v54, v54
	v_fmac_f32_e32 v75, v55, v55
	v_fmac_f32_e32 v75, v56, v56
	v_fmac_f32_e32 v75, v57, v57
	v_fmac_f32_e32 v75, v50, v50
	v_fmac_f32_e32 v75, v51, v51
	v_fmac_f32_e32 v75, v52, v52
	v_pk_mul_f32 v[82:83], v[66:67], v[66:67]
	v_fmac_f32_e32 v75, v53, v53
	v_add_f32_e32 v75, v75, v82
	v_pk_mul_f32 v[84:85], v[68:69], v[68:69]
	v_add_f32_e32 v75, v83, v75
	v_add_f32_e32 v75, v84, v75
	v_pk_mul_f32 v[86:87], v[70:71], v[70:71]
	v_add_f32_e32 v75, v85, v75
	v_add_f32_e32 v75, v86, v75
	v_pk_mul_f32 v[88:89], v[72:73], v[72:73]
	v_add_f32_e32 v75, v87, v75
	v_add_f32_e32 v75, v88, v75
	v_add_f32_e32 v75, v89, v75
	ds_bpermute_b32 v77, v146, v75
	v_mov_b64_e32 v[82:83], s[24:25]
	v_mov_b32_e32 v127, v163
	s_waitcnt lgkmcnt(0)
	v_add_f32_e32 v75, v75, v77
	ds_bpermute_b32 v77, v148, v75
	s_waitcnt lgkmcnt(0)
	v_add_f32_e32 v75, v75, v77
	v_fmamk_f32 v75, v75, 0x3c2aaaab, v1
	v_mul_f32_e32 v77, 0x4b800000, v75
	v_cmp_gt_f32_e32 vcc, s56, v75
	s_nop 1
	v_cndmask_b32_e32 v75, v75, v77, vcc
	v_rsq_f32_e32 v77, v75
	v_mad_i64_i32 v[74:75], s[30:31], v74, s57, v[82:83]
	v_lshl_add_u64 v[74:75], v[140:141], 1, v[74:75]
	v_mul_f32_e32 v84, 0x45800000, v77
	v_cndmask_b32_e32 v84, v77, v84, vcc
	v_mul_f32_e32 v62, v62, v84
	v_mul_f32_e32 v63, v63, v84
	v_lshl_add_u64 v[82:83], v[74:75], 0, v[126:127]
	v_mul_f32_e32 v64, v64, v84
	v_mul_f32_e32 v65, v65, v84
	v_mul_f32_e32 v58, v58, v84
	v_mul_f32_e32 v59, v59, v84
	v_mul_f32_e32 v60, v60, v84
	v_mul_f32_e32 v61, v61, v84
	v_mul_f32_e32 v54, v54, v84
	v_mul_f32_e32 v55, v55, v84
	v_mul_f32_e32 v56, v56, v84
	v_mul_f32_e32 v57, v57, v84
	v_mul_f32_e32 v50, v50, v84
	v_mul_f32_e32 v51, v51, v84
	v_mul_f32_e32 v52, v52, v84
	v_mul_f32_e32 v53, v53, v84
	s_and_b64 vcc, exec, s[6:7]
	v_mul_f32_e32 v62, v170, v62
	v_mul_f32_e32 v63, v171, v63
	v_mul_f32_e32 v64, v172, v64
	v_mul_f32_e32 v65, v173, v65
	v_cvt_pk_bf16_f32 v62, v62, v63
	v_cvt_pk_bf16_f32 v63, v64, v65
	global_store_dwordx2 v[82:83], v[62:63], off
	v_mul_f32_e32 v58, v174, v58
	v_mul_f32_e32 v59, v175, v59
	v_mul_f32_e32 v60, v176, v60
	v_mul_f32_e32 v61, v177, v61
	v_cvt_pk_bf16_f32 v58, v58, v59
	v_cvt_pk_bf16_f32 v59, v60, v61
	global_store_dwordx2 v[82:83], v[58:59], off offset:32
	v_mul_f32_e32 v54, v178, v54
	v_mul_f32_e32 v55, v179, v55
	v_mul_f32_e32 v56, v180, v56
	v_mul_f32_e32 v57, v57, v181
	v_cvt_pk_bf16_f32 v54, v54, v55
	v_cvt_pk_bf16_f32 v55, v56, v57
	global_store_dwordx2 v[82:83], v[54:55], off offset:64
	v_mul_f32_e32 v50, v50, v182
	v_mul_f32_e32 v51, v51, v183
	v_mul_f32_e32 v52, v52, v184
	v_mul_f32_e32 v53, v53, v185
	v_cvt_pk_bf16_f32 v50, v50, v51
	v_cvt_pk_bf16_f32 v51, v52, v53
	global_store_dwordx2 v[82:83], v[50:51], off offset:96
	s_nop 0
	v_mov_b32_e32 v50, v186
	v_mov_b32_e32 v51, v187
	v_mov_b32_e32 v52, v188
	v_mov_b32_e32 v53, v189
	v_pk_mul_f32 v[50:51], v[84:85], v[50:51] op_sel_hi:[0,1]
	v_pk_mul_f32 v[52:53], v[84:85], v[52:53] op_sel_hi:[0,1]
	v_pk_mul_f32 v[58:59], v[84:85], v[190:191] op_sel_hi:[0,1]
	v_pk_mul_f32 v[60:61], v[84:85], v[192:193] op_sel_hi:[0,1]
	v_pk_mul_f32 v[56:57], v[66:67], v[50:51]
	v_pk_mul_f32 v[54:55], v[68:69], v[52:53]
	v_pk_mul_f32 v[52:53], v[70:71], v[58:59]
	v_pk_mul_f32 v[50:51], v[72:73], v[60:61]
	s_cbranch_vccnz .LBB0_658
	v_add_u32_e32 v58, s60, v76
	v_ashrrev_i32_e32 v59, 6, v58
	v_and_b32_e32 v58, 63, v58
	v_cndmask_b32_e64 v58, v58, v59, s[4:5]
	v_cvt_f32_i32_e32 v66, v58
	ds_bpermute_b32 v58, v146, v56
	ds_bpermute_b32 v59, v146, v57
	v_mul_f32_e32 v61, 0x3ea1e89b, v66
	v_mul_f32_e32 v62, 0.15915494, v66
	v_mul_f32_e32 v63, 0.15915494, v61
	v_sin_f32_e32 v60, v62
	v_sin_f32_e32 v61, v63
	v_mul_f32_e32 v65, 0x3d0186e3, v66
	v_mul_f32_e32 v68, 0.15915494, v65
	v_cos_f32_e32 v62, v62
	s_waitcnt lgkmcnt(0)
	v_pk_mul_f32 v[58:59], v[60:61], v[58:59]
	v_mul_f32_e32 v61, 0x3dcccccd, v66
	ds_bpermute_b32 v60, v146, v54
	v_mul_f32_e32 v67, 0.15915494, v61
	ds_bpermute_b32 v61, v146, v55
	v_cos_f32_e32 v63, v63
	v_sin_f32_e32 v64, v67
	v_sin_f32_e32 v65, v68
	v_cndmask_b32_e64 v59, v59, -v59, s[2:3]
	v_cndmask_b32_e64 v58, v58, -v58, s[2:3]
	v_pk_fma_f32 v[56:57], v[62:63], v[56:57], v[58:59]
	s_waitcnt lgkmcnt(0)
	v_pk_mul_f32 v[60:61], v[64:65], v[60:61]
	v_mul_f32_e32 v63, 0x3c23d70b, v66
	v_mul_f32_e32 v65, 0x3b4f3e39, v66
	v_cos_f32_e32 v58, v67
	v_cos_f32_e32 v59, v68
	ds_bpermute_b32 v62, v146, v52
	v_mul_f32_e32 v67, 0.15915494, v63
	ds_bpermute_b32 v63, v146, v53
	v_mul_f32_e32 v68, 0.15915494, v65
	v_sin_f32_e32 v64, v67
	v_sin_f32_e32 v65, v68
	v_cndmask_b32_e64 v61, v61, -v61, s[2:3]
	v_cndmask_b32_e64 v60, v60, -v60, s[2:3]
	v_pk_fma_f32 v[54:55], v[58:59], v[54:55], v[60:61]
	v_cos_f32_e32 v58, v67
	v_cos_f32_e32 v59, v68
	s_waitcnt lgkmcnt(0)
	v_pk_mul_f32 v[60:61], v[64:65], v[62:63]
	v_mul_f32_e32 v63, 0x3a831270, v66
	v_mul_f32_e32 v65, 0x39a5cb61, v66
	ds_bpermute_b32 v62, v146, v50
	v_mul_f32_e32 v67, 0.15915494, v63
	ds_bpermute_b32 v63, v146, v51
	v_mul_f32_e32 v66, 0.15915494, v65
	v_sin_f32_e32 v64, v67
	v_sin_f32_e32 v65, v66
	v_cndmask_b32_e64 v61, v61, -v61, s[2:3]
	v_cndmask_b32_e64 v60, v60, -v60, s[2:3]
	v_pk_fma_f32 v[52:53], v[58:59], v[52:53], v[60:61]
	v_cos_f32_e32 v58, v67
	v_cos_f32_e32 v59, v66
	s_waitcnt lgkmcnt(0)
	v_pk_mul_f32 v[60:61], v[64:65], v[62:63]
	s_nop 0
	v_cndmask_b32_e64 v61, v61, -v61, s[2:3]
	v_cndmask_b32_e64 v60, v60, -v60, s[2:3]
	v_pk_fma_f32 v[50:51], v[58:59], v[50:51], v[60:61]
.LBB0_658:
	s_nop 0
	v_cvt_pk_bf16_f32 v59, v50, v51
	v_lshl_add_u64 v[50:51], v[74:75], 0, v[162:163]
	v_cvt_pk_bf16_f32 v56, v56, v57
	v_cvt_pk_bf16_f32 v57, v54, v55
	v_cvt_pk_bf16_f32 v58, v52, v53
	global_store_dwordx4 v[50:51], v[56:59], off offset:128
	v_or_b32_e32 v60, 0x50, v147
	s_cmp_gt_i32 s62, 1
	s_mov_b64 s[30:31], -1
	s_cbranch_scc0 .LBB0_660
	v_add_u32_e32 v50, s64, v60
	v_ashrrev_i32_e32 v51, 31, v50
	v_lshlrev_b64 v[50:51], 7, v[50:51]
	v_lshl_add_u64 v[50:51], s[22:23], 0, v[50:51]
	v_mov_b32_e32 v139, v163
	v_lshl_add_u64 v[50:51], v[50:51], 0, v[138:139]
	s_waitcnt vmcnt(29)
	v_mov_b32_e32 v54, v234
	v_mov_b32_e32 v55, v235
	v_mov_b32_e32 v56, v236
	v_mov_b32_e32 v57, v237
	s_nop 0
	v_mov_b32_e32 v50, v230
	v_mov_b32_e32 v51, v231
	v_mov_b32_e32 v52, v232
	v_mov_b32_e32 v53, v233
	s_mov_b64 s[30:31], 0
.LBB0_660:
	s_andn2_b64 vcc, exec, s[30:31]
	v_add_u32_e32 v58, s61, v60
	s_cbranch_vccnz .LBB0_664
	s_cmp_lg_u32 s62, 0
	v_mov_b32_e32 v50, v58
	s_cbranch_scc0 .LBB0_663
	v_add_u32_e32 v50, s63, v60
.LBB0_663:
	v_mov_b64_e32 v[52:53], s[14:15]
	v_mad_i64_i32 v[50:51], s[30:31], v50, s54, v[52:53]
	v_lshl_add_u64 v[50:51], v[50:51], 0, v[162:163]
	s_waitcnt vmcnt(27)
	v_mov_b32_e32 v54, v234
	v_mov_b32_e32 v55, v235
	v_mov_b32_e32 v56, v236
	v_mov_b32_e32 v57, v237
	v_lshlrev_b32_e32 v50, 16, v54
	v_and_b32_e32 v51, 0xffff0000, v54
	v_lshlrev_b32_e32 v52, 16, v55
	v_and_b32_e32 v53, 0xffff0000, v55
	v_lshlrev_b32_e32 v54, 16, v56
	v_and_b32_e32 v55, 0xffff0000, v56
	v_lshlrev_b32_e32 v56, 16, v57
	v_and_b32_e32 v57, 0xffff0000, v57
.LBB0_664:
	v_mul_f32_e32 v59, v47, v47
	v_fmac_f32_e32 v59, v46, v46
	v_fmac_f32_e32 v59, v48, v48
	v_fmac_f32_e32 v59, v49, v49
	v_fmac_f32_e32 v59, v42, v42
	v_fmac_f32_e32 v59, v43, v43
	v_fmac_f32_e32 v59, v44, v44
	v_fmac_f32_e32 v59, v45, v45
	v_fmac_f32_e32 v59, v38, v38
	v_fmac_f32_e32 v59, v39, v39
	v_fmac_f32_e32 v59, v40, v40
	v_fmac_f32_e32 v59, v41, v41
	v_fmac_f32_e32 v59, v34, v34
	v_fmac_f32_e32 v59, v35, v35
	v_fmac_f32_e32 v59, v36, v36
	v_pk_mul_f32 v[66:67], v[50:51], v[50:51]
	v_fmac_f32_e32 v59, v37, v37
	v_add_f32_e32 v59, v59, v66
	v_pk_mul_f32 v[68:69], v[52:53], v[52:53]
	v_add_f32_e32 v59, v67, v59
	v_add_f32_e32 v59, v68, v59
	v_pk_mul_f32 v[70:71], v[54:55], v[54:55]
	v_add_f32_e32 v59, v69, v59
	v_add_f32_e32 v59, v70, v59
	v_pk_mul_f32 v[72:73], v[56:57], v[56:57]
	v_add_f32_e32 v59, v71, v59
	v_add_f32_e32 v59, v72, v59
	v_add_f32_e32 v59, v73, v59
	ds_bpermute_b32 v61, v146, v59
	v_mov_b64_e32 v[66:67], s[24:25]
	v_mov_b32_e32 v127, v163
	s_waitcnt lgkmcnt(0)
	v_add_f32_e32 v59, v59, v61
	ds_bpermute_b32 v61, v148, v59
	s_waitcnt lgkmcnt(0)
	v_add_f32_e32 v59, v59, v61
	v_fmamk_f32 v59, v59, 0x3c2aaaab, v1
	v_mul_f32_e32 v61, 0x4b800000, v59
	v_cmp_gt_f32_e32 vcc, s56, v59
	s_nop 1
	v_cndmask_b32_e32 v59, v59, v61, vcc
	v_rsq_f32_e32 v61, v59
	v_mad_i64_i32 v[58:59], s[30:31], v58, s57, v[66:67]
	v_lshl_add_u64 v[58:59], v[140:141], 1, v[58:59]
	v_mul_f32_e32 v68, 0x45800000, v61
	v_cndmask_b32_e32 v68, v61, v68, vcc
	v_mul_f32_e32 v46, v46, v68
	v_mul_f32_e32 v47, v47, v68
	v_lshl_add_u64 v[66:67], v[58:59], 0, v[126:127]
	v_mul_f32_e32 v48, v48, v68
	v_mul_f32_e32 v49, v49, v68
	v_mul_f32_e32 v42, v42, v68
	v_mul_f32_e32 v43, v43, v68
	v_mul_f32_e32 v44, v44, v68
	v_mul_f32_e32 v45, v45, v68
	v_mul_f32_e32 v38, v38, v68
	v_mul_f32_e32 v39, v39, v68
	v_mul_f32_e32 v40, v40, v68
	v_mul_f32_e32 v41, v41, v68
	v_mul_f32_e32 v34, v34, v68
	v_mul_f32_e32 v35, v35, v68
	v_mul_f32_e32 v36, v36, v68
	v_mul_f32_e32 v37, v37, v68
	s_and_b64 vcc, exec, s[6:7]
	v_mul_f32_e32 v46, v170, v46
	v_mul_f32_e32 v47, v171, v47
	v_mul_f32_e32 v48, v172, v48
	v_mul_f32_e32 v49, v173, v49
	v_cvt_pk_bf16_f32 v46, v46, v47
	v_cvt_pk_bf16_f32 v47, v48, v49
	global_store_dwordx2 v[66:67], v[46:47], off
	v_mul_f32_e32 v42, v174, v42
	v_mul_f32_e32 v43, v175, v43
	v_mul_f32_e32 v44, v176, v44
	v_mul_f32_e32 v45, v177, v45
	v_cvt_pk_bf16_f32 v42, v42, v43
	v_cvt_pk_bf16_f32 v43, v44, v45
	global_store_dwordx2 v[66:67], v[42:43], off offset:32
	v_mul_f32_e32 v38, v178, v38
	v_mul_f32_e32 v39, v179, v39
	v_mul_f32_e32 v40, v180, v40
	v_mul_f32_e32 v41, v41, v181
	v_cvt_pk_bf16_f32 v38, v38, v39
	v_cvt_pk_bf16_f32 v39, v40, v41
	global_store_dwordx2 v[66:67], v[38:39], off offset:64
	v_mul_f32_e32 v34, v34, v182
	v_mul_f32_e32 v35, v35, v183
	v_mul_f32_e32 v36, v36, v184
	v_mul_f32_e32 v37, v37, v185
	v_cvt_pk_bf16_f32 v34, v34, v35
	v_cvt_pk_bf16_f32 v35, v36, v37
	global_store_dwordx2 v[66:67], v[34:35], off offset:96
	s_nop 0
	v_mov_b32_e32 v34, v186
	v_mov_b32_e32 v35, v187
	v_mov_b32_e32 v36, v188
	v_mov_b32_e32 v37, v189
	v_pk_mul_f32 v[34:35], v[68:69], v[34:35] op_sel_hi:[0,1]
	v_pk_mul_f32 v[36:37], v[68:69], v[36:37] op_sel_hi:[0,1]
	v_pk_mul_f32 v[42:43], v[68:69], v[190:191] op_sel_hi:[0,1]
	v_pk_mul_f32 v[44:45], v[68:69], v[192:193] op_sel_hi:[0,1]
	v_pk_mul_f32 v[40:41], v[50:51], v[34:35]
	v_pk_mul_f32 v[38:39], v[52:53], v[36:37]
	v_pk_mul_f32 v[36:37], v[54:55], v[42:43]
	v_pk_mul_f32 v[34:35], v[56:57], v[44:45]
	s_cbranch_vccnz .LBB0_666
	v_add_u32_e32 v42, s60, v60
	v_ashrrev_i32_e32 v43, 6, v42
	v_and_b32_e32 v42, 63, v42
	v_cndmask_b32_e64 v42, v42, v43, s[4:5]
	v_cvt_f32_i32_e32 v50, v42
	ds_bpermute_b32 v42, v146, v40
	ds_bpermute_b32 v43, v146, v41
	v_mul_f32_e32 v45, 0x3ea1e89b, v50
	v_mul_f32_e32 v46, 0.15915494, v50
	v_mul_f32_e32 v47, 0.15915494, v45
	v_sin_f32_e32 v44, v46
	v_sin_f32_e32 v45, v47
	v_mul_f32_e32 v49, 0x3d0186e3, v50
	v_mul_f32_e32 v52, 0.15915494, v49
	v_cos_f32_e32 v46, v46
	s_waitcnt lgkmcnt(0)
	v_pk_mul_f32 v[42:43], v[44:45], v[42:43]
	v_mul_f32_e32 v45, 0x3dcccccd, v50
	ds_bpermute_b32 v44, v146, v38
	v_mul_f32_e32 v51, 0.15915494, v45
	ds_bpermute_b32 v45, v146, v39
	v_cos_f32_e32 v47, v47
	v_sin_f32_e32 v48, v51
	v_sin_f32_e32 v49, v52
	v_cndmask_b32_e64 v43, v43, -v43, s[2:3]
	v_cndmask_b32_e64 v42, v42, -v42, s[2:3]
	v_pk_fma_f32 v[40:41], v[46:47], v[40:41], v[42:43]
	s_waitcnt lgkmcnt(0)
	v_pk_mul_f32 v[44:45], v[48:49], v[44:45]
	v_mul_f32_e32 v47, 0x3c23d70b, v50
	v_mul_f32_e32 v49, 0x3b4f3e39, v50
	v_cos_f32_e32 v42, v51
	v_cos_f32_e32 v43, v52
	ds_bpermute_b32 v46, v146, v36
	v_mul_f32_e32 v51, 0.15915494, v47
	ds_bpermute_b32 v47, v146, v37
	v_mul_f32_e32 v52, 0.15915494, v49
	v_sin_f32_e32 v48, v51
	v_sin_f32_e32 v49, v52
	v_cndmask_b32_e64 v45, v45, -v45, s[2:3]
	v_cndmask_b32_e64 v44, v44, -v44, s[2:3]
	v_pk_fma_f32 v[38:39], v[42:43], v[38:39], v[44:45]
	v_cos_f32_e32 v42, v51
	v_cos_f32_e32 v43, v52
	s_waitcnt lgkmcnt(0)
	v_pk_mul_f32 v[44:45], v[48:49], v[46:47]
	v_mul_f32_e32 v47, 0x3a831270, v50
	v_mul_f32_e32 v49, 0x39a5cb61, v50
	ds_bpermute_b32 v46, v146, v34
	v_mul_f32_e32 v51, 0.15915494, v47
	ds_bpermute_b32 v47, v146, v35
	v_mul_f32_e32 v50, 0.15915494, v49
	v_sin_f32_e32 v48, v51
	v_sin_f32_e32 v49, v50
	v_cndmask_b32_e64 v45, v45, -v45, s[2:3]
	v_cndmask_b32_e64 v44, v44, -v44, s[2:3]
	v_pk_fma_f32 v[36:37], v[42:43], v[36:37], v[44:45]
	v_cos_f32_e32 v42, v51
	v_cos_f32_e32 v43, v50
	s_waitcnt lgkmcnt(0)
	v_pk_mul_f32 v[44:45], v[48:49], v[46:47]
	s_nop 0
	v_cndmask_b32_e64 v45, v45, -v45, s[2:3]
	v_cndmask_b32_e64 v44, v44, -v44, s[2:3]
	v_pk_fma_f32 v[34:35], v[42:43], v[34:35], v[44:45]
.LBB0_666:
	s_nop 0
	v_cvt_pk_bf16_f32 v43, v34, v35
	v_lshl_add_u64 v[34:35], v[58:59], 0, v[162:163]
	v_cvt_pk_bf16_f32 v40, v40, v41
	v_cvt_pk_bf16_f32 v41, v38, v39
	v_cvt_pk_bf16_f32 v42, v36, v37
	global_store_dwordx4 v[34:35], v[40:43], off offset:128
	v_or_b32_e32 v44, 0x60, v147
	s_cmp_gt_i32 s62, 1
	s_mov_b64 s[30:31], -1
	s_cbranch_scc0 .LBB0_668
	v_add_u32_e32 v34, s64, v44
	v_ashrrev_i32_e32 v35, 31, v34
	v_lshlrev_b64 v[34:35], 7, v[34:35]
	v_lshl_add_u64 v[34:35], s[22:23], 0, v[34:35]
	v_mov_b32_e32 v139, v163
	v_lshl_add_u64 v[34:35], v[34:35], 0, v[138:139]
	s_waitcnt vmcnt(32)
	v_mov_b32_e32 v38, v242
	v_mov_b32_e32 v39, v243
	v_mov_b32_e32 v40, v244
	v_mov_b32_e32 v41, v245
	s_nop 0
	v_mov_b32_e32 v34, v238
	v_mov_b32_e32 v35, v239
	v_mov_b32_e32 v36, v240
	v_mov_b32_e32 v37, v241
	s_mov_b64 s[30:31], 0
.LBB0_668:
	s_andn2_b64 vcc, exec, s[30:31]
	v_add_u32_e32 v42, s61, v44
	s_cbranch_vccnz .LBB0_672
	s_cmp_lg_u32 s62, 0
	v_mov_b32_e32 v34, v42
	s_cbranch_scc0 .LBB0_671
	v_add_u32_e32 v34, s63, v44
.LBB0_671:
	v_mov_b64_e32 v[36:37], s[14:15]
	v_mad_i64_i32 v[34:35], s[30:31], v34, s54, v[36:37]
	v_lshl_add_u64 v[34:35], v[34:35], 0, v[162:163]
	s_waitcnt vmcnt(31)
	v_mov_b32_e32 v38, v242
	v_mov_b32_e32 v39, v243
	v_mov_b32_e32 v40, v244
	v_mov_b32_e32 v41, v245
	v_lshlrev_b32_e32 v34, 16, v38
	v_and_b32_e32 v35, 0xffff0000, v38
	v_lshlrev_b32_e32 v36, 16, v39
	v_and_b32_e32 v37, 0xffff0000, v39
	v_lshlrev_b32_e32 v38, 16, v40
	v_and_b32_e32 v39, 0xffff0000, v40
	v_lshlrev_b32_e32 v40, 16, v41
	v_and_b32_e32 v41, 0xffff0000, v41
.LBB0_672:
	v_mul_f32_e32 v43, v31, v31
	v_fmac_f32_e32 v43, v30, v30
	v_fmac_f32_e32 v43, v32, v32
	v_fmac_f32_e32 v43, v33, v33
	v_fmac_f32_e32 v43, v26, v26
	v_fmac_f32_e32 v43, v27, v27
	v_fmac_f32_e32 v43, v28, v28
	v_fmac_f32_e32 v43, v29, v29
	v_fmac_f32_e32 v43, v22, v22
	v_fmac_f32_e32 v43, v23, v23
	v_fmac_f32_e32 v43, v24, v24
	v_fmac_f32_e32 v43, v25, v25
	v_fmac_f32_e32 v43, v18, v18
	v_fmac_f32_e32 v43, v19, v19
	v_fmac_f32_e32 v43, v20, v20
	v_pk_mul_f32 v[50:51], v[34:35], v[34:35]
	v_fmac_f32_e32 v43, v21, v21
	v_add_f32_e32 v43, v43, v50
	v_pk_mul_f32 v[52:53], v[36:37], v[36:37]
	v_add_f32_e32 v43, v51, v43
	v_add_f32_e32 v43, v52, v43
	v_pk_mul_f32 v[54:55], v[38:39], v[38:39]
	v_add_f32_e32 v43, v53, v43
	v_add_f32_e32 v43, v54, v43
	v_pk_mul_f32 v[56:57], v[40:41], v[40:41]
	v_add_f32_e32 v43, v55, v43
	v_add_f32_e32 v43, v56, v43
	v_add_f32_e32 v43, v57, v43
	ds_bpermute_b32 v45, v146, v43
	v_mov_b64_e32 v[50:51], s[24:25]
	v_mov_b32_e32 v127, v163
	s_waitcnt lgkmcnt(0)
	v_add_f32_e32 v43, v43, v45
	ds_bpermute_b32 v45, v148, v43
	s_waitcnt lgkmcnt(0)
	v_add_f32_e32 v43, v43, v45
	v_fmamk_f32 v43, v43, 0x3c2aaaab, v1
	v_mul_f32_e32 v45, 0x4b800000, v43
	v_cmp_gt_f32_e32 vcc, s56, v43
	s_nop 1
	v_cndmask_b32_e32 v43, v43, v45, vcc
	v_rsq_f32_e32 v45, v43
	v_mad_i64_i32 v[42:43], s[30:31], v42, s57, v[50:51]
	v_lshl_add_u64 v[42:43], v[140:141], 1, v[42:43]
	v_mul_f32_e32 v52, 0x45800000, v45
	v_cndmask_b32_e32 v52, v45, v52, vcc
	v_mul_f32_e32 v30, v30, v52
	v_mul_f32_e32 v31, v31, v52
	v_lshl_add_u64 v[50:51], v[42:43], 0, v[126:127]
	v_mul_f32_e32 v32, v32, v52
	v_mul_f32_e32 v33, v33, v52
	v_mul_f32_e32 v26, v26, v52
	v_mul_f32_e32 v27, v27, v52
	v_mul_f32_e32 v28, v28, v52
	v_mul_f32_e32 v29, v29, v52
	v_mul_f32_e32 v22, v22, v52
	v_mul_f32_e32 v23, v23, v52
	v_mul_f32_e32 v24, v24, v52
	v_mul_f32_e32 v25, v25, v52
	v_mul_f32_e32 v18, v18, v52
	v_mul_f32_e32 v19, v19, v52
	v_mul_f32_e32 v20, v20, v52
	v_mul_f32_e32 v21, v21, v52
	s_and_b64 vcc, exec, s[6:7]
	v_mul_f32_e32 v30, v170, v30
	v_mul_f32_e32 v31, v171, v31
	v_mul_f32_e32 v32, v172, v32
	v_mul_f32_e32 v33, v173, v33
	v_cvt_pk_bf16_f32 v30, v30, v31
	v_cvt_pk_bf16_f32 v31, v32, v33
	global_store_dwordx2 v[50:51], v[30:31], off
	v_mul_f32_e32 v26, v174, v26
	v_mul_f32_e32 v27, v175, v27
	v_mul_f32_e32 v28, v176, v28
	v_mul_f32_e32 v29, v177, v29
	v_cvt_pk_bf16_f32 v26, v26, v27
	v_cvt_pk_bf16_f32 v27, v28, v29
	global_store_dwordx2 v[50:51], v[26:27], off offset:32
	v_mul_f32_e32 v22, v178, v22
	v_mul_f32_e32 v23, v179, v23
	v_mul_f32_e32 v24, v180, v24
	v_mul_f32_e32 v25, v25, v181
	v_cvt_pk_bf16_f32 v22, v22, v23
	v_cvt_pk_bf16_f32 v23, v24, v25
	global_store_dwordx2 v[50:51], v[22:23], off offset:64
	v_mul_f32_e32 v18, v18, v182
	v_mul_f32_e32 v19, v19, v183
	v_mul_f32_e32 v20, v20, v184
	v_mul_f32_e32 v21, v21, v185
	v_cvt_pk_bf16_f32 v18, v18, v19
	v_cvt_pk_bf16_f32 v19, v20, v21
	global_store_dwordx2 v[50:51], v[18:19], off offset:96
	s_nop 0
	v_mov_b32_e32 v18, v186
	v_mov_b32_e32 v19, v187
	v_mov_b32_e32 v20, v188
	v_mov_b32_e32 v21, v189
	v_pk_mul_f32 v[18:19], v[52:53], v[18:19] op_sel_hi:[0,1]
	v_pk_mul_f32 v[20:21], v[52:53], v[20:21] op_sel_hi:[0,1]
	v_pk_mul_f32 v[26:27], v[52:53], v[190:191] op_sel_hi:[0,1]
	v_pk_mul_f32 v[28:29], v[52:53], v[192:193] op_sel_hi:[0,1]
	v_pk_mul_f32 v[24:25], v[34:35], v[18:19]
	v_pk_mul_f32 v[22:23], v[36:37], v[20:21]
	v_pk_mul_f32 v[20:21], v[38:39], v[26:27]
	v_pk_mul_f32 v[18:19], v[40:41], v[28:29]
	s_cbranch_vccnz .LBB0_674
	v_add_u32_e32 v26, s60, v44
	v_ashrrev_i32_e32 v27, 6, v26
	v_and_b32_e32 v26, 63, v26
	v_cndmask_b32_e64 v26, v26, v27, s[4:5]
	v_cvt_f32_i32_e32 v34, v26
	ds_bpermute_b32 v26, v146, v24
	ds_bpermute_b32 v27, v146, v25
	v_mul_f32_e32 v29, 0x3ea1e89b, v34
	v_mul_f32_e32 v30, 0.15915494, v34
	v_mul_f32_e32 v31, 0.15915494, v29
	v_sin_f32_e32 v28, v30
	v_sin_f32_e32 v29, v31
	v_mul_f32_e32 v33, 0x3d0186e3, v34
	v_mul_f32_e32 v36, 0.15915494, v33
	v_cos_f32_e32 v30, v30
	s_waitcnt lgkmcnt(0)
	v_pk_mul_f32 v[26:27], v[28:29], v[26:27]
	v_mul_f32_e32 v29, 0x3dcccccd, v34
	ds_bpermute_b32 v28, v146, v22
	v_mul_f32_e32 v35, 0.15915494, v29
	ds_bpermute_b32 v29, v146, v23
	v_cos_f32_e32 v31, v31
	v_sin_f32_e32 v32, v35
	v_sin_f32_e32 v33, v36
	v_cndmask_b32_e64 v27, v27, -v27, s[2:3]
	v_cndmask_b32_e64 v26, v26, -v26, s[2:3]
	v_pk_fma_f32 v[24:25], v[30:31], v[24:25], v[26:27]
	s_waitcnt lgkmcnt(0)
	v_pk_mul_f32 v[28:29], v[32:33], v[28:29]
	v_mul_f32_e32 v31, 0x3c23d70b, v34
	v_mul_f32_e32 v33, 0x3b4f3e39, v34
	v_cos_f32_e32 v26, v35
	v_cos_f32_e32 v27, v36
	ds_bpermute_b32 v30, v146, v20
	v_mul_f32_e32 v35, 0.15915494, v31
	ds_bpermute_b32 v31, v146, v21
	v_mul_f32_e32 v36, 0.15915494, v33
	v_sin_f32_e32 v32, v35
	v_sin_f32_e32 v33, v36
	v_cndmask_b32_e64 v29, v29, -v29, s[2:3]
	v_cndmask_b32_e64 v28, v28, -v28, s[2:3]
	v_pk_fma_f32 v[22:23], v[26:27], v[22:23], v[28:29]
	v_cos_f32_e32 v26, v35
	v_cos_f32_e32 v27, v36
	s_waitcnt lgkmcnt(0)
	v_pk_mul_f32 v[28:29], v[32:33], v[30:31]
	v_mul_f32_e32 v31, 0x3a831270, v34
	v_mul_f32_e32 v33, 0x39a5cb61, v34
	ds_bpermute_b32 v30, v146, v18
	v_mul_f32_e32 v35, 0.15915494, v31
	ds_bpermute_b32 v31, v146, v19
	v_mul_f32_e32 v34, 0.15915494, v33
	v_sin_f32_e32 v32, v35
	v_sin_f32_e32 v33, v34
	v_cndmask_b32_e64 v29, v29, -v29, s[2:3]
	v_cndmask_b32_e64 v28, v28, -v28, s[2:3]
	v_pk_fma_f32 v[20:21], v[26:27], v[20:21], v[28:29]
	v_cos_f32_e32 v26, v35
	v_cos_f32_e32 v27, v34
	s_waitcnt lgkmcnt(0)
	v_pk_mul_f32 v[28:29], v[32:33], v[30:31]
	s_nop 0
	v_cndmask_b32_e64 v29, v29, -v29, s[2:3]
	v_cndmask_b32_e64 v28, v28, -v28, s[2:3]
	v_pk_fma_f32 v[18:19], v[26:27], v[18:19], v[28:29]
.LBB0_674:
	s_nop 0
	v_cvt_pk_bf16_f32 v27, v18, v19
	v_lshl_add_u64 v[18:19], v[42:43], 0, v[162:163]
	v_cvt_pk_bf16_f32 v24, v24, v25
	v_cvt_pk_bf16_f32 v25, v22, v23
	v_cvt_pk_bf16_f32 v26, v20, v21
	global_store_dwordx4 v[18:19], v[24:27], off offset:128
	v_or_b32_e32 v28, 0x70, v147
	s_cmp_gt_i32 s62, 1
	s_mov_b64 s[30:31], -1
	s_cbranch_scc0 .LBB0_676
	v_add_u32_e32 v18, s64, v28
	v_ashrrev_i32_e32 v19, 31, v18
	v_lshlrev_b64 v[18:19], 7, v[18:19]
	v_lshl_add_u64 v[18:19], s[22:23], 0, v[18:19]
	v_mov_b32_e32 v139, v163
	v_lshl_add_u64 v[18:19], v[18:19], 0, v[138:139]
	s_waitcnt vmcnt(35)
	v_mov_b32_e32 v22, v250
	v_mov_b32_e32 v23, v251
	v_mov_b32_e32 v24, v252
	v_mov_b32_e32 v25, v253
	s_nop 0
	v_mov_b32_e32 v18, v246
	v_mov_b32_e32 v19, v247
	v_mov_b32_e32 v20, v248
	v_mov_b32_e32 v21, v249
	s_mov_b64 s[30:31], 0
.LBB0_676:
	s_andn2_b64 vcc, exec, s[30:31]
	v_add_u32_e32 v26, s61, v28
	s_cbranch_vccnz .LBB0_680
	s_cmp_lg_u32 s62, 0
	v_mov_b32_e32 v18, v26
	s_cbranch_scc0 .LBB0_679
	v_add_u32_e32 v18, s63, v28
.LBB0_679:
	v_mov_b64_e32 v[20:21], s[14:15]
	v_mad_i64_i32 v[18:19], s[30:31], v18, s54, v[20:21]
	v_lshl_add_u64 v[18:19], v[18:19], 0, v[162:163]
	s_waitcnt vmcnt(35)
	v_mov_b32_e32 v22, v250
	v_mov_b32_e32 v23, v251
	v_mov_b32_e32 v24, v252
	v_mov_b32_e32 v25, v253
	v_lshlrev_b32_e32 v18, 16, v22
	v_and_b32_e32 v19, 0xffff0000, v22
	v_lshlrev_b32_e32 v20, 16, v23
	v_and_b32_e32 v21, 0xffff0000, v23
	v_lshlrev_b32_e32 v22, 16, v24
	v_and_b32_e32 v23, 0xffff0000, v24
	v_lshlrev_b32_e32 v24, 16, v25
	v_and_b32_e32 v25, 0xffff0000, v25
.LBB0_680:
	v_mul_f32_e32 v27, v15, v15
	v_fmac_f32_e32 v27, v14, v14
	v_fmac_f32_e32 v27, v16, v16
	v_fmac_f32_e32 v27, v17, v17
	v_fmac_f32_e32 v27, v10, v10
	v_fmac_f32_e32 v27, v11, v11
	v_fmac_f32_e32 v27, v12, v12
	v_fmac_f32_e32 v27, v13, v13
	v_fmac_f32_e32 v27, v6, v6
	v_fmac_f32_e32 v27, v7, v7
	v_fmac_f32_e32 v27, v8, v8
	v_fmac_f32_e32 v27, v9, v9
	v_fmac_f32_e32 v27, v2, v2
	v_fmac_f32_e32 v27, v3, v3
	v_fmac_f32_e32 v27, v4, v4
	v_pk_mul_f32 v[34:35], v[18:19], v[18:19]
	v_fmac_f32_e32 v27, v5, v5
	v_add_f32_e32 v27, v27, v34
	v_pk_mul_f32 v[36:37], v[20:21], v[20:21]
	v_add_f32_e32 v27, v35, v27
	v_add_f32_e32 v27, v36, v27
	v_pk_mul_f32 v[38:39], v[22:23], v[22:23]
	v_add_f32_e32 v27, v37, v27
	v_add_f32_e32 v27, v38, v27
	v_pk_mul_f32 v[40:41], v[24:25], v[24:25]
	v_add_f32_e32 v27, v39, v27
	v_add_f32_e32 v27, v40, v27
	v_add_f32_e32 v27, v41, v27
	ds_bpermute_b32 v29, v146, v27
	v_mov_b64_e32 v[34:35], s[24:25]
	v_mov_b32_e32 v127, v163
	s_waitcnt lgkmcnt(0)
	v_add_f32_e32 v27, v27, v29
	ds_bpermute_b32 v29, v148, v27
	s_waitcnt lgkmcnt(0)
	v_add_f32_e32 v27, v27, v29
	v_fmamk_f32 v27, v27, 0x3c2aaaab, v1
	v_mul_f32_e32 v29, 0x4b800000, v27
	v_cmp_gt_f32_e32 vcc, s56, v27
	s_nop 1
	v_cndmask_b32_e32 v27, v27, v29, vcc
	v_rsq_f32_e32 v29, v27
	v_mad_i64_i32 v[26:27], s[30:31], v26, s57, v[34:35]
	v_lshl_add_u64 v[26:27], v[140:141], 1, v[26:27]
	v_mul_f32_e32 v36, 0x45800000, v29
	v_cndmask_b32_e32 v36, v29, v36, vcc
	v_mul_f32_e32 v14, v14, v36
	v_mul_f32_e32 v15, v15, v36
	v_lshl_add_u64 v[34:35], v[26:27], 0, v[126:127]
	v_mul_f32_e32 v16, v16, v36
	v_mul_f32_e32 v17, v17, v36
	v_mul_f32_e32 v10, v10, v36
	v_mul_f32_e32 v11, v11, v36
	v_mul_f32_e32 v12, v12, v36
	v_mul_f32_e32 v13, v13, v36
	v_mul_f32_e32 v6, v6, v36
	v_mul_f32_e32 v7, v7, v36
	v_mul_f32_e32 v8, v8, v36
	v_mul_f32_e32 v9, v9, v36
	v_mul_f32_e32 v2, v2, v36
	v_mul_f32_e32 v3, v3, v36
	v_mul_f32_e32 v4, v4, v36
	v_mul_f32_e32 v5, v5, v36
	s_and_b64 vcc, exec, s[6:7]
	v_mul_f32_e32 v14, v170, v14
	v_mul_f32_e32 v15, v171, v15
	v_mul_f32_e32 v16, v172, v16
	v_mul_f32_e32 v17, v173, v17
	v_cvt_pk_bf16_f32 v14, v14, v15
	v_cvt_pk_bf16_f32 v15, v16, v17
	global_store_dwordx2 v[34:35], v[14:15], off
	v_mul_f32_e32 v10, v174, v10
	v_mul_f32_e32 v11, v175, v11
	v_mul_f32_e32 v12, v176, v12
	v_mul_f32_e32 v13, v177, v13
	v_cvt_pk_bf16_f32 v10, v10, v11
	v_cvt_pk_bf16_f32 v11, v12, v13
	global_store_dwordx2 v[34:35], v[10:11], off offset:32
	v_mul_f32_e32 v6, v178, v6
	v_mul_f32_e32 v7, v179, v7
	v_mul_f32_e32 v8, v180, v8
	v_mul_f32_e32 v9, v9, v181
	v_cvt_pk_bf16_f32 v6, v6, v7
	v_cvt_pk_bf16_f32 v7, v8, v9
	global_store_dwordx2 v[34:35], v[6:7], off offset:64
	v_mul_f32_e32 v2, v2, v182
	v_mul_f32_e32 v3, v3, v183
	v_mul_f32_e32 v4, v4, v184
	v_mul_f32_e32 v5, v5, v185
	v_cvt_pk_bf16_f32 v2, v2, v3
	v_cvt_pk_bf16_f32 v3, v4, v5
	global_store_dwordx2 v[34:35], v[2:3], off offset:96
	s_nop 0
	v_mov_b32_e32 v2, v186
	v_mov_b32_e32 v3, v187
	v_mov_b32_e32 v4, v188
	v_mov_b32_e32 v5, v189
	v_pk_mul_f32 v[2:3], v[36:37], v[2:3] op_sel_hi:[0,1]
	v_pk_mul_f32 v[4:5], v[36:37], v[4:5] op_sel_hi:[0,1]
	v_pk_mul_f32 v[10:11], v[36:37], v[190:191] op_sel_hi:[0,1]
	v_pk_mul_f32 v[12:13], v[36:37], v[192:193] op_sel_hi:[0,1]
	v_pk_mul_f32 v[8:9], v[18:19], v[2:3]
	v_pk_mul_f32 v[6:7], v[20:21], v[4:5]
	v_pk_mul_f32 v[4:5], v[22:23], v[10:11]
	v_pk_mul_f32 v[2:3], v[24:25], v[12:13]
	s_cbranch_vccnz .LBB0_682
	v_add_u32_e32 v10, s60, v28
	v_ashrrev_i32_e32 v11, 6, v10
	v_and_b32_e32 v10, 63, v10
	v_cndmask_b32_e64 v10, v10, v11, s[4:5]
	v_cvt_f32_i32_e32 v18, v10
	ds_bpermute_b32 v10, v146, v8
	ds_bpermute_b32 v11, v146, v9
	v_mul_f32_e32 v13, 0x3ea1e89b, v18
	v_mul_f32_e32 v14, 0.15915494, v18
	v_mul_f32_e32 v15, 0.15915494, v13
	v_sin_f32_e32 v12, v14
	v_sin_f32_e32 v13, v15
	v_mul_f32_e32 v17, 0x3d0186e3, v18
	v_mul_f32_e32 v20, 0.15915494, v17
	v_cos_f32_e32 v14, v14
	s_waitcnt lgkmcnt(0)
	v_pk_mul_f32 v[10:11], v[12:13], v[10:11]
	v_mul_f32_e32 v13, 0x3dcccccd, v18
	ds_bpermute_b32 v12, v146, v6
	v_mul_f32_e32 v19, 0.15915494, v13
	ds_bpermute_b32 v13, v146, v7
	v_cos_f32_e32 v15, v15
	v_sin_f32_e32 v16, v19
	v_sin_f32_e32 v17, v20
	v_cndmask_b32_e64 v11, v11, -v11, s[2:3]
	v_cndmask_b32_e64 v10, v10, -v10, s[2:3]
	v_pk_fma_f32 v[8:9], v[14:15], v[8:9], v[10:11]
	s_waitcnt lgkmcnt(0)
	v_pk_mul_f32 v[12:13], v[16:17], v[12:13]
	v_mul_f32_e32 v15, 0x3c23d70b, v18
	v_mul_f32_e32 v17, 0x3b4f3e39, v18
	v_cos_f32_e32 v10, v19
	v_cos_f32_e32 v11, v20
	ds_bpermute_b32 v14, v146, v4
	v_mul_f32_e32 v19, 0.15915494, v15
	ds_bpermute_b32 v15, v146, v5
	v_mul_f32_e32 v20, 0.15915494, v17
	v_sin_f32_e32 v16, v19
	v_sin_f32_e32 v17, v20
	v_cndmask_b32_e64 v13, v13, -v13, s[2:3]
	v_cndmask_b32_e64 v12, v12, -v12, s[2:3]
	v_pk_fma_f32 v[6:7], v[10:11], v[6:7], v[12:13]
	v_cos_f32_e32 v10, v19
	v_cos_f32_e32 v11, v20
	s_waitcnt lgkmcnt(0)
	v_pk_mul_f32 v[12:13], v[16:17], v[14:15]
	v_mul_f32_e32 v15, 0x3a831270, v18
	v_mul_f32_e32 v17, 0x39a5cb61, v18
	ds_bpermute_b32 v14, v146, v2
	v_mul_f32_e32 v19, 0.15915494, v15
	ds_bpermute_b32 v15, v146, v3
	v_mul_f32_e32 v18, 0.15915494, v17
	v_sin_f32_e32 v16, v19
	v_sin_f32_e32 v17, v18
	v_cndmask_b32_e64 v13, v13, -v13, s[2:3]
	v_cndmask_b32_e64 v12, v12, -v12, s[2:3]
	v_pk_fma_f32 v[4:5], v[10:11], v[4:5], v[12:13]
	v_cos_f32_e32 v10, v19
	v_cos_f32_e32 v11, v18
	s_waitcnt lgkmcnt(0)
	v_pk_mul_f32 v[12:13], v[16:17], v[14:15]
	s_nop 0
	v_cndmask_b32_e64 v13, v13, -v13, s[2:3]
	v_cndmask_b32_e64 v12, v12, -v12, s[2:3]
	v_pk_fma_f32 v[2:3], v[10:11], v[2:3], v[12:13]

.LBB0_1861:
	s_lshl_b32 s2, s4, 9
	v_and_b32_e32 v130, 15, v151
	v_bfe_u32 v150, v151, 4, 2
	v_ashrrev_i32_e32 v131, 1, v151
	s_add_i32 s2, s60, s2
	v_and_or_b32 v147, v131, s51, v130
	s_add_i32 s5, s2, 0xfffff800
	v_lshlrev_b32_e32 v142, 3, v150
	v_mov_b32_e32 v194, 0x180
	v_bfe_u32 v196, v0, 4, 2
	v_lshlrev_b32_e32 v196, 4, v196
	v_add_u32_e32 v194, v194, v196
	v_mov_b32_e32 v195, 0x280
	v_bfe_u32 v196, v0, 4, 2
	v_lshlrev_b32_e32 v196, 5, v196
	v_add_u32_e32 v195, v195, v196
	global_load_dwordx4 v[170:173], v194, s[20:21]
	global_load_dwordx4 v[174:177], v194, s[20:21] offset:64
	global_load_dwordx4 v[178:181], v194, s[20:21] offset:128
	global_load_dwordx4 v[182:185], v194, s[20:21] offset:192
	global_load_dwordx4 v[186:189], v195, s[20:21]
	global_load_dwordx4 v[190:193], v195, s[20:21] offset:16
	s_mov_b64 s[2:3], -1
	s_cmp_gt_i32 s62, 1
	v_add_u32_e32 v148, s5, v147
	v_lshlrev_b32_e32 v138, 2, v142
	s_cbranch_scc0 .LBB0_1863
	v_add_u32_e32 v130, 0x100, v148
	v_ashrrev_i32_e32 v131, 31, v130
	v_lshlrev_b64 v[130:131], 7, v[130:131]
	v_lshl_add_u64 v[130:131], s[22:23], 0, v[130:131]
	v_mov_b32_e32 v139, v163
	v_lshl_add_u64 v[130:131], v[130:131], 0, v[138:139]
	v_mov_b32_e32 v164, v130
	v_mov_b32_e32 v165, v131
	global_load_dwordx4 v[134:137], v[130:131], off offset:16
	s_nop 0
	global_load_dwordx4 v[130:133], v[130:131], off
	s_mov_b64 s[2:3], 0x1000
	global_load_dwordx4 v[198:201], v[164:165], off offset:2064
	global_load_dwordx4 v[152:155], v[164:165], off offset:2048
	v_lshl_add_u64 v[164:165], v[164:165], 0, s[2:3]
	global_load_dwordx4 v[206:209], v[164:165], off offset:16
	global_load_dwordx4 v[202:205], v[164:165], off
	global_load_dwordx4 v[214:217], v[164:165], off offset:2064
	global_load_dwordx4 v[210:213], v[164:165], off offset:2048
	v_lshl_add_u64 v[164:165], v[164:165], 0, s[2:3]
	global_load_dwordx4 v[226:229], v[164:165], off offset:16
	global_load_dwordx4 v[218:221], v[164:165], off
	global_load_dwordx4 v[234:237], v[164:165], off offset:2064
	global_load_dwordx4 v[230:233], v[164:165], off offset:2048
	v_lshl_add_u64 v[164:165], v[164:165], 0, s[2:3]
	global_load_dwordx4 v[242:245], v[164:165], off offset:16
	global_load_dwordx4 v[238:241], v[164:165], off
	global_load_dwordx4 v[250:253], v[164:165], off offset:2064
	global_load_dwordx4 v[246:249], v[164:165], off offset:2048
	s_mov_b64 s[2:3], 0

.LBB0_1867:
	v_lshlrev_b32_e32 v162, 4, v150
	v_mul_f32_e32 v168, v127, v127
	v_fmac_f32_e32 v168, v126, v126
	v_fmac_f32_e32 v168, v128, v128
	v_fmac_f32_e32 v168, v129, v129
	v_fmac_f32_e32 v168, v122, v122
	v_fmac_f32_e32 v168, v123, v123
	v_fmac_f32_e32 v168, v124, v124
	v_fmac_f32_e32 v168, v125, v125
	v_fmac_f32_e32 v168, v118, v118
	v_fmac_f32_e32 v168, v119, v119
	v_fmac_f32_e32 v168, v120, v120
	v_fmac_f32_e32 v168, v121, v121
	v_fmac_f32_e32 v168, v114, v114
	v_fmac_f32_e32 v168, v115, v115
	v_fmac_f32_e32 v168, v116, v116
	s_waitcnt vmcnt(14)
	v_pk_mul_f32 v[140:141], v[130:131], v[130:131]
	v_fmac_f32_e32 v168, v117, v117
	v_add_f32_e32 v140, v168, v140
	v_pk_mul_f32 v[144:145], v[132:133], v[132:133]
	v_add_f32_e32 v140, v141, v140
	v_add_f32_e32 v140, v144, v140
	v_and_b32_e32 v146, 64, v166
	v_pk_mul_f32 v[156:157], v[134:135], v[134:135]
	v_add_f32_e32 v140, v145, v140
	v_xor_b32_e32 v143, 16, v166
	v_add_u32_e32 v169, 64, v146
	v_add_f32_e32 v140, v156, v140
	v_pk_mul_f32 v[158:159], v[136:137], v[136:137]
	v_cmp_lt_i32_e32 vcc, v143, v169
	v_add_f32_e32 v140, v157, v140
	v_add_f32_e32 v140, v158, v140
	v_cndmask_b32_e32 v143, v166, v143, vcc
	v_lshlrev_b32_e32 v146, 2, v143
	v_add_f32_e32 v140, v159, v140
	ds_bpermute_b32 v141, v146, v140
	v_xor_b32_e32 v149, 32, v166
	v_cmp_lt_i32_e32 vcc, v149, v169
	v_lshrrev_b32_e32 v167, 6, v151
	s_lshl_b32 s2, s58, 2
	v_cndmask_b32_e32 v144, v166, v149, vcc
	v_lshlrev_b32_e32 v149, 2, v144
	s_waitcnt lgkmcnt(0)
	v_add_f32_e32 v141, v140, v141
	ds_bpermute_b32 v156, v149, v141
	v_mov_b64_e32 v[160:161], s[24:25]
	v_and_or_b32 v140, v167, 3, s2
	v_mad_i64_i32 v[144:145], s[2:3], v139, s57, v[160:161]
	s_waitcnt lgkmcnt(0)
	v_add_f32_e32 v139, v141, v156
	v_fmamk_f32 v139, v139, 0x3c2aaaab, v1
	v_mul_f32_e32 v141, 0x4b800000, v139
	v_cmp_gt_f32_e32 vcc, s56, v139
	v_mul_lo_u32 v140, v140, s55
	v_mov_b32_e32 v143, v163
	v_cndmask_b32_e32 v139, v139, v141, vcc
	v_rsq_f32_e32 v139, v139
	v_ashrrev_i32_e32 v141, 31, v140
	v_lshl_add_u64 v[144:145], v[140:141], 1, v[144:145]
	v_lshl_add_u64 v[156:157], v[144:145], 0, v[142:143]
	v_mul_f32_e32 v143, 0x45800000, v139
	v_cndmask_b32_e32 v158, v139, v143, vcc
	v_mul_f32_e32 v126, v126, v158
	v_mul_f32_e32 v127, v127, v158
	v_mul_f32_e32 v128, v128, v158
	v_mul_f32_e32 v129, v129, v158
	v_mul_f32_e32 v122, v122, v158
	v_mul_f32_e32 v123, v123, v158
	v_mul_f32_e32 v124, v124, v158
	v_mul_f32_e32 v125, v125, v158
	v_mul_f32_e32 v118, v118, v158
	v_mul_f32_e32 v119, v119, v158
	v_mul_f32_e32 v120, v120, v158
	v_mul_f32_e32 v121, v121, v158
	v_mul_f32_e32 v114, v114, v158
	v_mul_f32_e32 v115, v115, v158
	v_mul_f32_e32 v116, v116, v158
	v_mul_f32_e32 v117, v117, v158
	s_cmp_eq_u32 s62, 1
	v_cmp_gt_u32_e64 s[4:5], 2, v150
	s_cselect_b64 s[30:31], -1, 0
	v_mul_f32_e32 v126, v170, v126
	v_mul_f32_e32 v127, v171, v127
	v_mul_f32_e32 v128, v172, v128
	v_mul_f32_e32 v129, v173, v129
	v_cvt_pk_bf16_f32 v126, v126, v127
	v_cvt_pk_bf16_f32 v127, v128, v129
	global_store_dwordx2 v[156:157], v[126:127], off
	s_cmp_lg_u32 s62, 1
	v_mul_f32_e32 v122, v174, v122
	v_mul_f32_e32 v123, v175, v123
	v_mul_f32_e32 v124, v176, v124
	v_mul_f32_e32 v125, v177, v125
	v_cvt_pk_bf16_f32 v122, v122, v123
	v_cvt_pk_bf16_f32 v123, v124, v125
	global_store_dwordx2 v[156:157], v[122:123], off offset:32
	v_mul_f32_e32 v118, v178, v118
	v_mul_f32_e32 v119, v179, v119
	v_mul_f32_e32 v120, v180, v120
	v_mul_f32_e32 v121, v121, v181
	v_cvt_pk_bf16_f32 v118, v118, v119
	v_cvt_pk_bf16_f32 v119, v120, v121
	global_store_dwordx2 v[156:157], v[118:119], off offset:64
	v_and_b32_e32 v122, 16, v151
	v_cmp_eq_u32_e64 s[2:3], 0, v122
	v_mul_f32_e32 v114, v114, v182
	v_mul_f32_e32 v115, v115, v183
	v_mul_f32_e32 v116, v116, v184
	v_mul_f32_e32 v117, v117, v185
	v_cvt_pk_bf16_f32 v114, v114, v115
	v_cvt_pk_bf16_f32 v115, v116, v117
	global_store_dwordx2 v[156:157], v[114:115], off offset:96
	s_nop 0
	v_mov_b32_e32 v114, v186
	v_mov_b32_e32 v115, v187
	v_mov_b32_e32 v116, v188
	v_mov_b32_e32 v117, v189
	v_pk_mul_f32 v[114:115], v[158:159], v[114:115] op_sel_hi:[0,1]
	v_pk_mul_f32 v[116:117], v[158:159], v[116:117] op_sel_hi:[0,1]
	v_pk_mul_f32 v[122:123], v[158:159], v[190:191] op_sel_hi:[0,1]
	v_pk_mul_f32 v[124:125], v[158:159], v[192:193] op_sel_hi:[0,1]
	v_pk_mul_f32 v[120:121], v[130:131], v[114:115]
	v_pk_mul_f32 v[118:119], v[132:133], v[116:117]
	v_pk_mul_f32 v[116:117], v[134:135], v[122:123]
	v_pk_mul_f32 v[114:115], v[136:137], v[124:125]
	s_cbranch_scc1 .LBB0_1869
	v_add_u32_e32 v122, s60, v147
	v_ashrrev_i32_e32 v123, 6, v122
	v_and_b32_e32 v122, 63, v122
	v_cndmask_b32_e64 v122, v122, v123, s[4:5]
	v_cvt_f32_i32_e32 v130, v122
	ds_bpermute_b32 v122, v146, v120
	ds_bpermute_b32 v123, v146, v121
	v_mul_f32_e32 v125, 0x3ea1e89b, v130
	v_mul_f32_e32 v126, 0.15915494, v130
	v_mul_f32_e32 v127, 0.15915494, v125
	v_sin_f32_e32 v124, v126
	v_sin_f32_e32 v125, v127
	v_mul_f32_e32 v129, 0x3d0186e3, v130
	v_mul_f32_e32 v132, 0.15915494, v129
	v_cos_f32_e32 v126, v126
	s_waitcnt lgkmcnt(0)
	v_pk_mul_f32 v[122:123], v[124:125], v[122:123]
	v_mul_f32_e32 v125, 0x3dcccccd, v130
	ds_bpermute_b32 v124, v146, v118
	v_mul_f32_e32 v131, 0.15915494, v125
	ds_bpermute_b32 v125, v146, v119
	v_cos_f32_e32 v127, v127
	v_sin_f32_e32 v128, v131
	v_sin_f32_e32 v129, v132
	v_cndmask_b32_e64 v123, v123, -v123, s[2:3]
	v_cndmask_b32_e64 v122, v122, -v122, s[2:3]
	v_pk_fma_f32 v[120:121], v[126:127], v[120:121], v[122:123]
	s_waitcnt lgkmcnt(0)
	v_pk_mul_f32 v[124:125], v[128:129], v[124:125]
	v_mul_f32_e32 v127, 0x3c23d70b, v130
	v_mul_f32_e32 v129, 0x3b4f3e39, v130
	v_cos_f32_e32 v122, v131
	v_cos_f32_e32 v123, v132
	ds_bpermute_b32 v126, v146, v116
	v_mul_f32_e32 v131, 0.15915494, v127
	ds_bpermute_b32 v127, v146, v117
	v_mul_f32_e32 v132, 0.15915494, v129
	v_sin_f32_e32 v128, v131
	v_sin_f32_e32 v129, v132
	v_cndmask_b32_e64 v125, v125, -v125, s[2:3]
	v_cndmask_b32_e64 v124, v124, -v124, s[2:3]
	v_pk_fma_f32 v[118:119], v[122:123], v[118:119], v[124:125]
	v_cos_f32_e32 v122, v131
	v_cos_f32_e32 v123, v132
	s_waitcnt lgkmcnt(0)
	v_pk_mul_f32 v[124:125], v[128:129], v[126:127]
	v_mul_f32_e32 v127, 0x3a831270, v130
	v_mul_f32_e32 v129, 0x39a5cb61, v130
	ds_bpermute_b32 v126, v146, v114
	v_mul_f32_e32 v131, 0.15915494, v127
	ds_bpermute_b32 v127, v146, v115
	v_mul_f32_e32 v130, 0.15915494, v129
	v_sin_f32_e32 v128, v131
	v_sin_f32_e32 v129, v130
	v_cndmask_b32_e64 v125, v125, -v125, s[2:3]
	v_cndmask_b32_e64 v124, v124, -v124, s[2:3]
	v_pk_fma_f32 v[116:117], v[122:123], v[116:117], v[124:125]
	v_cos_f32_e32 v122, v131
	v_cos_f32_e32 v123, v130
	s_waitcnt lgkmcnt(0)
	v_pk_mul_f32 v[124:125], v[128:129], v[126:127]
	s_nop 0
	v_cndmask_b32_e64 v125, v125, -v125, s[2:3]
	v_cndmask_b32_e64 v124, v124, -v124, s[2:3]
	v_pk_fma_f32 v[114:115], v[122:123], v[114:115], v[124:125]
.LBB0_1869:
	v_lshl_add_u64 v[124:125], s[20:21], 0, v[162:163]
	v_lshlrev_b32_e32 v162, 1, v142
	v_cvt_pk_bf16_f32 v131, v114, v115
	v_lshl_add_u64 v[114:115], v[144:145], 0, v[162:163]
	v_cvt_pk_bf16_f32 v128, v120, v121
	v_cvt_pk_bf16_f32 v129, v118, v119
	v_cvt_pk_bf16_f32 v130, v116, v117
	global_store_dwordx4 v[114:115], v[128:131], off offset:128
	v_mov_b32_e32 v139, v163
	v_lshlrev_b32_e32 v126, 2, v150
	v_lshl_add_u64 v[122:123], s[20:21], 0, v[138:139]
	s_cmp_gt_i32 s62, 1
	s_mov_b64 s[6:7], -1
	s_cbranch_scc0 .LBB0_1871
	v_add_u32_e32 v114, 0x110, v148
	v_ashrrev_i32_e32 v115, 31, v114
	v_lshlrev_b64 v[114:115], 7, v[114:115]
	v_lshl_add_u64 v[114:115], s[22:23], 0, v[114:115]
	v_mov_b32_e32 v139, v163
	v_lshl_add_u64 v[114:115], v[114:115], 0, v[138:139]
	s_waitcnt vmcnt(17)
	v_mov_b32_e32 v118, v198
	v_mov_b32_e32 v119, v199
	v_mov_b32_e32 v120, v200
	v_mov_b32_e32 v121, v201
	s_nop 0
	v_mov_b32_e32 v114, v152
	v_mov_b32_e32 v115, v153
	v_mov_b32_e32 v116, v154
	v_mov_b32_e32 v117, v155
	s_mov_b64 s[6:7], 0
.LBB0_1871:
	v_or_b32_e32 v130, 16, v147
	s_andn2_b64 vcc, exec, s[6:7]
	v_add_u32_e32 v128, s61, v130
	s_cbranch_vccnz .LBB0_1875
	s_cmp_lg_u32 s62, 0
	v_mov_b32_e32 v114, v128
	s_cbranch_scc0 .LBB0_1874
	v_add_u32_e32 v114, s63, v130

.LBB0_1875:
	v_mul_f32_e32 v127, v111, v111
	v_fmac_f32_e32 v127, v110, v110
	v_fmac_f32_e32 v127, v112, v112
	v_fmac_f32_e32 v127, v113, v113
	v_fmac_f32_e32 v127, v106, v106
	v_fmac_f32_e32 v127, v107, v107
	v_fmac_f32_e32 v127, v108, v108
	v_fmac_f32_e32 v127, v109, v109
	v_fmac_f32_e32 v127, v102, v102
	v_fmac_f32_e32 v127, v103, v103
	v_fmac_f32_e32 v127, v104, v104
	v_fmac_f32_e32 v127, v105, v105
	v_fmac_f32_e32 v127, v98, v98
	v_fmac_f32_e32 v127, v99, v99
	v_fmac_f32_e32 v127, v100, v100
	v_pk_mul_f32 v[136:137], v[114:115], v[114:115]
	v_fmac_f32_e32 v127, v101, v101
	v_add_f32_e32 v127, v127, v136
	v_pk_mul_f32 v[142:143], v[116:117], v[116:117]
	v_add_f32_e32 v127, v137, v127
	v_add_f32_e32 v127, v142, v127
	v_pk_mul_f32 v[144:145], v[118:119], v[118:119]
	v_add_f32_e32 v127, v143, v127
	v_add_f32_e32 v127, v144, v127
	v_pk_mul_f32 v[150:151], v[120:121], v[120:121]
	v_add_f32_e32 v127, v145, v127
	v_add_f32_e32 v127, v150, v127
	v_add_f32_e32 v127, v151, v127
	ds_bpermute_b32 v129, v146, v127
	v_mov_b64_e32 v[136:137], s[24:25]
	v_lshlrev_b32_e32 v126, 1, v126
	s_waitcnt lgkmcnt(0)
	v_add_f32_e32 v129, v127, v129
	ds_bpermute_b32 v131, v149, v129
	v_mov_b32_e32 v127, v163
	s_waitcnt lgkmcnt(0)
	v_add_f32_e32 v129, v129, v131
	v_fmamk_f32 v129, v129, 0x3c2aaaab, v1
	v_mul_f32_e32 v131, 0x4b800000, v129
	v_cmp_gt_f32_e32 vcc, s56, v129
	s_nop 1
	v_cndmask_b32_e32 v129, v129, v131, vcc
	v_rsq_f32_e32 v131, v129
	v_mad_i64_i32 v[128:129], s[6:7], v128, s57, v[136:137]
	v_lshl_add_u64 v[128:129], v[140:141], 1, v[128:129]
	v_lshl_add_u64 v[136:137], v[128:129], 0, v[126:127]
	v_mul_f32_e32 v127, 0x45800000, v131
	v_cndmask_b32_e32 v142, v131, v127, vcc
	v_mul_f32_e32 v110, v110, v142
	v_mul_f32_e32 v111, v111, v142
	v_mul_f32_e32 v112, v112, v142
	v_mul_f32_e32 v113, v113, v142
	v_mul_f32_e32 v106, v106, v142
	v_mul_f32_e32 v107, v107, v142
	v_mul_f32_e32 v108, v108, v142
	v_mul_f32_e32 v109, v109, v142
	v_mul_f32_e32 v102, v102, v142
	v_mul_f32_e32 v103, v103, v142
	v_mul_f32_e32 v104, v104, v142
	v_mul_f32_e32 v105, v105, v142
	v_mul_f32_e32 v98, v98, v142
	v_mul_f32_e32 v99, v99, v142
	v_mul_f32_e32 v100, v100, v142
	v_mul_f32_e32 v101, v101, v142
	s_andn2_b64 vcc, exec, s[30:31]
	v_mul_f32_e32 v110, v170, v110
	v_mul_f32_e32 v111, v171, v111
	v_mul_f32_e32 v112, v172, v112
	v_mul_f32_e32 v113, v173, v113
	v_cvt_pk_bf16_f32 v110, v110, v111
	v_cvt_pk_bf16_f32 v111, v112, v113
	global_store_dwordx2 v[136:137], v[110:111], off
	v_mul_f32_e32 v106, v174, v106
	v_mul_f32_e32 v107, v175, v107
	v_mul_f32_e32 v108, v176, v108
	v_mul_f32_e32 v109, v177, v109
	v_cvt_pk_bf16_f32 v106, v106, v107
	v_cvt_pk_bf16_f32 v107, v108, v109
	global_store_dwordx2 v[136:137], v[106:107], off offset:32
	v_mul_f32_e32 v102, v178, v102
	v_mul_f32_e32 v103, v179, v103
	v_mul_f32_e32 v104, v180, v104
	v_mul_f32_e32 v105, v105, v181
	v_cvt_pk_bf16_f32 v102, v102, v103
	v_cvt_pk_bf16_f32 v103, v104, v105
	global_store_dwordx2 v[136:137], v[102:103], off offset:64
	v_cndmask_b32_e64 v106, 0, 1, s[30:31]
	v_cmp_ne_u32_e64 s[6:7], 1, v106
	v_mul_f32_e32 v98, v98, v182
	v_mul_f32_e32 v99, v99, v183
	v_mul_f32_e32 v100, v100, v184
	v_mul_f32_e32 v101, v101, v185
	v_cvt_pk_bf16_f32 v98, v98, v99
	v_cvt_pk_bf16_f32 v99, v100, v101
	global_store_dwordx2 v[136:137], v[98:99], off offset:96
	s_nop 0
	v_mov_b32_e32 v98, v186
	v_mov_b32_e32 v99, v187
	v_mov_b32_e32 v100, v188
	v_mov_b32_e32 v101, v189
	v_pk_mul_f32 v[98:99], v[142:143], v[98:99] op_sel_hi:[0,1]
	v_pk_mul_f32 v[100:101], v[142:143], v[100:101] op_sel_hi:[0,1]
	v_pk_mul_f32 v[106:107], v[142:143], v[190:191] op_sel_hi:[0,1]
	v_pk_mul_f32 v[108:109], v[142:143], v[192:193] op_sel_hi:[0,1]
	v_pk_mul_f32 v[104:105], v[114:115], v[98:99]
	v_pk_mul_f32 v[102:103], v[116:117], v[100:101]
	v_pk_mul_f32 v[100:101], v[118:119], v[106:107]
	v_pk_mul_f32 v[98:99], v[120:121], v[108:109]
	s_cbranch_vccnz .LBB0_1877
	v_add_u32_e32 v106, s60, v130
	v_ashrrev_i32_e32 v107, 6, v106
	v_and_b32_e32 v106, 63, v106
	v_cndmask_b32_e64 v106, v106, v107, s[4:5]
	v_cvt_f32_i32_e32 v114, v106
	ds_bpermute_b32 v106, v146, v104
	ds_bpermute_b32 v107, v146, v105
	v_mul_f32_e32 v109, 0x3ea1e89b, v114
	v_mul_f32_e32 v110, 0.15915494, v114
	v_mul_f32_e32 v111, 0.15915494, v109
	v_sin_f32_e32 v108, v110
	v_sin_f32_e32 v109, v111
	v_mul_f32_e32 v113, 0x3d0186e3, v114
	v_mul_f32_e32 v116, 0.15915494, v113
	v_cos_f32_e32 v110, v110
	s_waitcnt lgkmcnt(0)
	v_pk_mul_f32 v[106:107], v[108:109], v[106:107]
	v_mul_f32_e32 v109, 0x3dcccccd, v114
	ds_bpermute_b32 v108, v146, v102
	v_mul_f32_e32 v115, 0.15915494, v109
	ds_bpermute_b32 v109, v146, v103
	v_cos_f32_e32 v111, v111
	v_sin_f32_e32 v112, v115
	v_sin_f32_e32 v113, v116
	v_cndmask_b32_e64 v107, v107, -v107, s[2:3]
	v_cndmask_b32_e64 v106, v106, -v106, s[2:3]
	v_pk_fma_f32 v[104:105], v[110:111], v[104:105], v[106:107]
	s_waitcnt lgkmcnt(0)
	v_pk_mul_f32 v[108:109], v[112:113], v[108:109]
	v_mul_f32_e32 v111, 0x3c23d70b, v114
	v_mul_f32_e32 v113, 0x3b4f3e39, v114
	v_cos_f32_e32 v106, v115
	v_cos_f32_e32 v107, v116
	ds_bpermute_b32 v110, v146, v100
	v_mul_f32_e32 v115, 0.15915494, v111
	ds_bpermute_b32 v111, v146, v101
	v_mul_f32_e32 v116, 0.15915494, v113
	v_sin_f32_e32 v112, v115
	v_sin_f32_e32 v113, v116
	v_cndmask_b32_e64 v109, v109, -v109, s[2:3]
	v_cndmask_b32_e64 v108, v108, -v108, s[2:3]
	v_pk_fma_f32 v[102:103], v[106:107], v[102:103], v[108:109]
	v_cos_f32_e32 v106, v115
	v_cos_f32_e32 v107, v116
	s_waitcnt lgkmcnt(0)
	v_pk_mul_f32 v[108:109], v[112:113], v[110:111]
	v_mul_f32_e32 v111, 0x3a831270, v114
	v_mul_f32_e32 v113, 0x39a5cb61, v114
	ds_bpermute_b32 v110, v146, v98
	v_mul_f32_e32 v115, 0.15915494, v111
	ds_bpermute_b32 v111, v146, v99
	v_mul_f32_e32 v114, 0.15915494, v113
	v_sin_f32_e32 v112, v115
	v_sin_f32_e32 v113, v114
	v_cndmask_b32_e64 v109, v109, -v109, s[2:3]
	v_cndmask_b32_e64 v108, v108, -v108, s[2:3]
	v_pk_fma_f32 v[100:101], v[106:107], v[100:101], v[108:109]
	v_cos_f32_e32 v106, v115
	v_cos_f32_e32 v107, v114
	s_waitcnt lgkmcnt(0)
	v_pk_mul_f32 v[108:109], v[112:113], v[110:111]
	s_nop 0
	v_cndmask_b32_e64 v109, v109, -v109, s[2:3]
	v_cndmask_b32_e64 v108, v108, -v108, s[2:3]
	v_pk_fma_f32 v[98:99], v[106:107], v[98:99], v[108:109]
.LBB0_1877:
	s_nop 0
	v_cvt_pk_bf16_f32 v107, v98, v99
	v_lshl_add_u64 v[98:99], v[128:129], 0, v[162:163]
	v_cvt_pk_bf16_f32 v104, v104, v105
	v_cvt_pk_bf16_f32 v105, v102, v103
	v_cvt_pk_bf16_f32 v106, v100, v101
	global_store_dwordx4 v[98:99], v[104:107], off offset:128
	s_cmp_gt_i32 s62, 1
	s_mov_b64 s[30:31], -1
	s_cbranch_scc0 .LBB0_1879
	v_add_u32_e32 v98, 0x120, v148
	v_ashrrev_i32_e32 v99, 31, v98
	v_lshlrev_b64 v[98:99], 7, v[98:99]
	v_lshl_add_u64 v[98:99], s[22:23], 0, v[98:99]
	v_mov_b32_e32 v139, v163
	v_lshl_add_u64 v[98:99], v[98:99], 0, v[138:139]
	s_waitcnt vmcnt(20)
	v_mov_b32_e32 v102, v206
	v_mov_b32_e32 v103, v207
	v_mov_b32_e32 v104, v208
	v_mov_b32_e32 v105, v209
	s_nop 0
	v_mov_b32_e32 v98, v202
	v_mov_b32_e32 v99, v203
	v_mov_b32_e32 v100, v204
	v_mov_b32_e32 v101, v205
	s_mov_b64 s[30:31], 0
.LBB0_1879:
	v_or_b32_e32 v108, 32, v147
	s_andn2_b64 vcc, exec, s[30:31]
	v_add_u32_e32 v106, s61, v108
	s_cbranch_vccnz .LBB0_1883
	s_cmp_lg_u32 s62, 0
	v_mov_b32_e32 v98, v106
	s_cbranch_scc0 .LBB0_1882
	v_add_u32_e32 v98, s63, v108

.LBB0_1883:
	v_mul_f32_e32 v107, v95, v95
	v_fmac_f32_e32 v107, v94, v94
	v_fmac_f32_e32 v107, v96, v96
	v_fmac_f32_e32 v107, v97, v97
	v_fmac_f32_e32 v107, v90, v90
	v_fmac_f32_e32 v107, v91, v91
	v_fmac_f32_e32 v107, v92, v92
	v_fmac_f32_e32 v107, v93, v93
	v_fmac_f32_e32 v107, v86, v86
	v_fmac_f32_e32 v107, v87, v87
	v_fmac_f32_e32 v107, v88, v88
	v_fmac_f32_e32 v107, v89, v89
	v_fmac_f32_e32 v107, v82, v82
	v_fmac_f32_e32 v107, v83, v83
	v_fmac_f32_e32 v107, v84, v84
	v_pk_mul_f32 v[114:115], v[98:99], v[98:99]
	v_fmac_f32_e32 v107, v85, v85
	v_add_f32_e32 v107, v107, v114
	v_pk_mul_f32 v[116:117], v[100:101], v[100:101]
	v_add_f32_e32 v107, v115, v107
	v_add_f32_e32 v107, v116, v107
	v_pk_mul_f32 v[118:119], v[102:103], v[102:103]
	v_add_f32_e32 v107, v117, v107
	v_add_f32_e32 v107, v118, v107
	v_pk_mul_f32 v[120:121], v[104:105], v[104:105]
	v_add_f32_e32 v107, v119, v107
	v_add_f32_e32 v107, v120, v107
	v_add_f32_e32 v107, v121, v107
	ds_bpermute_b32 v109, v146, v107
	v_mov_b64_e32 v[114:115], s[24:25]
	v_mov_b32_e32 v127, v163
	s_waitcnt lgkmcnt(0)
	v_add_f32_e32 v107, v107, v109
	ds_bpermute_b32 v109, v149, v107
	s_waitcnt lgkmcnt(0)
	v_add_f32_e32 v107, v107, v109
	v_fmamk_f32 v107, v107, 0x3c2aaaab, v1
	v_mul_f32_e32 v109, 0x4b800000, v107
	v_cmp_gt_f32_e32 vcc, s56, v107
	s_nop 1
	v_cndmask_b32_e32 v107, v107, v109, vcc
	v_rsq_f32_e32 v109, v107
	v_mad_i64_i32 v[106:107], s[30:31], v106, s57, v[114:115]
	v_lshl_add_u64 v[106:107], v[140:141], 1, v[106:107]
	v_mul_f32_e32 v116, 0x45800000, v109
	v_cndmask_b32_e32 v116, v109, v116, vcc
	v_mul_f32_e32 v94, v94, v116
	v_mul_f32_e32 v95, v95, v116
	v_lshl_add_u64 v[114:115], v[106:107], 0, v[126:127]
	v_mul_f32_e32 v96, v96, v116
	v_mul_f32_e32 v97, v97, v116
	v_mul_f32_e32 v90, v90, v116
	v_mul_f32_e32 v91, v91, v116
	v_mul_f32_e32 v92, v92, v116
	v_mul_f32_e32 v93, v93, v116
	v_mul_f32_e32 v86, v86, v116
	v_mul_f32_e32 v87, v87, v116
	v_mul_f32_e32 v88, v88, v116
	v_mul_f32_e32 v89, v89, v116
	v_mul_f32_e32 v82, v82, v116
	v_mul_f32_e32 v83, v83, v116
	v_mul_f32_e32 v84, v84, v116
	v_mul_f32_e32 v85, v85, v116
	s_and_b64 vcc, exec, s[6:7]
	v_mul_f32_e32 v94, v170, v94
	v_mul_f32_e32 v95, v171, v95
	v_mul_f32_e32 v96, v172, v96
	v_mul_f32_e32 v97, v173, v97
	v_cvt_pk_bf16_f32 v94, v94, v95
	v_cvt_pk_bf16_f32 v95, v96, v97
	global_store_dwordx2 v[114:115], v[94:95], off
	v_mul_f32_e32 v90, v174, v90
	v_mul_f32_e32 v91, v175, v91
	v_mul_f32_e32 v92, v176, v92
	v_mul_f32_e32 v93, v177, v93
	v_cvt_pk_bf16_f32 v90, v90, v91
	v_cvt_pk_bf16_f32 v91, v92, v93
	global_store_dwordx2 v[114:115], v[90:91], off offset:32
	v_mul_f32_e32 v86, v178, v86
	v_mul_f32_e32 v87, v179, v87
	v_mul_f32_e32 v88, v180, v88
	v_mul_f32_e32 v89, v89, v181
	v_cvt_pk_bf16_f32 v86, v86, v87
	v_cvt_pk_bf16_f32 v87, v88, v89
	global_store_dwordx2 v[114:115], v[86:87], off offset:64
	v_mul_f32_e32 v82, v82, v182
	v_mul_f32_e32 v83, v83, v183
	v_mul_f32_e32 v84, v84, v184
	v_mul_f32_e32 v85, v85, v185
	v_cvt_pk_bf16_f32 v82, v82, v83
	v_cvt_pk_bf16_f32 v83, v84, v85
	global_store_dwordx2 v[114:115], v[82:83], off offset:96
	s_nop 0
	v_mov_b32_e32 v82, v186
	v_mov_b32_e32 v83, v187
	v_mov_b32_e32 v84, v188
	v_mov_b32_e32 v85, v189
	v_pk_mul_f32 v[82:83], v[116:117], v[82:83] op_sel_hi:[0,1]
	v_pk_mul_f32 v[84:85], v[116:117], v[84:85] op_sel_hi:[0,1]
	v_pk_mul_f32 v[90:91], v[116:117], v[190:191] op_sel_hi:[0,1]
	v_pk_mul_f32 v[92:93], v[116:117], v[192:193] op_sel_hi:[0,1]
	v_pk_mul_f32 v[88:89], v[98:99], v[82:83]
	v_pk_mul_f32 v[86:87], v[100:101], v[84:85]
	v_pk_mul_f32 v[84:85], v[102:103], v[90:91]
	v_pk_mul_f32 v[82:83], v[104:105], v[92:93]
	s_cbranch_vccnz .LBB0_1885
	v_add_u32_e32 v90, s60, v108
	v_ashrrev_i32_e32 v91, 6, v90
	v_and_b32_e32 v90, 63, v90
	v_cndmask_b32_e64 v90, v90, v91, s[4:5]
	v_cvt_f32_i32_e32 v98, v90
	ds_bpermute_b32 v90, v146, v88
	ds_bpermute_b32 v91, v146, v89
	v_mul_f32_e32 v93, 0x3ea1e89b, v98
	v_mul_f32_e32 v94, 0.15915494, v98
	v_mul_f32_e32 v95, 0.15915494, v93
	v_sin_f32_e32 v92, v94
	v_sin_f32_e32 v93, v95
	v_mul_f32_e32 v97, 0x3d0186e3, v98
	v_mul_f32_e32 v100, 0.15915494, v97
	v_cos_f32_e32 v94, v94
	s_waitcnt lgkmcnt(0)
	v_pk_mul_f32 v[90:91], v[92:93], v[90:91]
	v_mul_f32_e32 v93, 0x3dcccccd, v98
	ds_bpermute_b32 v92, v146, v86
	v_mul_f32_e32 v99, 0.15915494, v93
	ds_bpermute_b32 v93, v146, v87
	v_cos_f32_e32 v95, v95
	v_sin_f32_e32 v96, v99
	v_sin_f32_e32 v97, v100
	v_cndmask_b32_e64 v91, v91, -v91, s[2:3]
	v_cndmask_b32_e64 v90, v90, -v90, s[2:3]
	v_pk_fma_f32 v[88:89], v[94:95], v[88:89], v[90:91]
	s_waitcnt lgkmcnt(0)
	v_pk_mul_f32 v[92:93], v[96:97], v[92:93]
	v_mul_f32_e32 v95, 0x3c23d70b, v98
	v_mul_f32_e32 v97, 0x3b4f3e39, v98
	v_cos_f32_e32 v90, v99
	v_cos_f32_e32 v91, v100
	ds_bpermute_b32 v94, v146, v84
	v_mul_f32_e32 v99, 0.15915494, v95
	ds_bpermute_b32 v95, v146, v85
	v_mul_f32_e32 v100, 0.15915494, v97
	v_sin_f32_e32 v96, v99
	v_sin_f32_e32 v97, v100
	v_cndmask_b32_e64 v93, v93, -v93, s[2:3]
	v_cndmask_b32_e64 v92, v92, -v92, s[2:3]
	v_pk_fma_f32 v[86:87], v[90:91], v[86:87], v[92:93]
	v_cos_f32_e32 v90, v99
	v_cos_f32_e32 v91, v100
	s_waitcnt lgkmcnt(0)
	v_pk_mul_f32 v[92:93], v[96:97], v[94:95]
	v_mul_f32_e32 v95, 0x3a831270, v98
	v_mul_f32_e32 v97, 0x39a5cb61, v98
	ds_bpermute_b32 v94, v146, v82
	v_mul_f32_e32 v99, 0.15915494, v95
	ds_bpermute_b32 v95, v146, v83
	v_mul_f32_e32 v98, 0.15915494, v97
	v_sin_f32_e32 v96, v99
	v_sin_f32_e32 v97, v98
	v_cndmask_b32_e64 v93, v93, -v93, s[2:3]
	v_cndmask_b32_e64 v92, v92, -v92, s[2:3]
	v_pk_fma_f32 v[84:85], v[90:91], v[84:85], v[92:93]
	v_cos_f32_e32 v90, v99
	v_cos_f32_e32 v91, v98
	s_waitcnt lgkmcnt(0)
	v_pk_mul_f32 v[92:93], v[96:97], v[94:95]
	s_nop 0
	v_cndmask_b32_e64 v93, v93, -v93, s[2:3]
	v_cndmask_b32_e64 v92, v92, -v92, s[2:3]
	v_pk_fma_f32 v[82:83], v[90:91], v[82:83], v[92:93]
.LBB0_1885:
	s_nop 0
	v_cvt_pk_bf16_f32 v91, v82, v83
	v_lshl_add_u64 v[82:83], v[106:107], 0, v[162:163]
	v_cvt_pk_bf16_f32 v88, v88, v89
	v_cvt_pk_bf16_f32 v89, v86, v87
	v_cvt_pk_bf16_f32 v90, v84, v85
	global_store_dwordx4 v[82:83], v[88:91], off offset:128
	s_cmp_gt_i32 s62, 1
	s_mov_b64 s[30:31], -1
	s_cbranch_scc0 .LBB0_1887
	v_add_u32_e32 v82, 0x130, v148
	v_ashrrev_i32_e32 v83, 31, v82
	v_lshlrev_b64 v[82:83], 7, v[82:83]
	v_lshl_add_u64 v[82:83], s[22:23], 0, v[82:83]
	v_mov_b32_e32 v139, v163
	v_lshl_add_u64 v[82:83], v[82:83], 0, v[138:139]
	s_waitcnt vmcnt(23)
	v_mov_b32_e32 v86, v214
	v_mov_b32_e32 v87, v215
	v_mov_b32_e32 v88, v216
	v_mov_b32_e32 v89, v217
	s_nop 0
	v_mov_b32_e32 v82, v210
	v_mov_b32_e32 v83, v211
	v_mov_b32_e32 v84, v212
	v_mov_b32_e32 v85, v213
	s_mov_b64 s[30:31], 0
.LBB0_1887:
	v_or_b32_e32 v92, 48, v147
	s_andn2_b64 vcc, exec, s[30:31]
	v_add_u32_e32 v90, s61, v92
	s_cbranch_vccnz .LBB0_1891
	s_cmp_lg_u32 s62, 0
	v_mov_b32_e32 v82, v90
	s_cbranch_scc0 .LBB0_1890
	v_add_u32_e32 v82, s63, v92

.LBB0_1891:
	v_mul_f32_e32 v91, v79, v79
	v_fmac_f32_e32 v91, v78, v78
	v_fmac_f32_e32 v91, v80, v80
	v_fmac_f32_e32 v91, v81, v81
	v_fmac_f32_e32 v91, v74, v74
	v_fmac_f32_e32 v91, v75, v75
	v_fmac_f32_e32 v91, v76, v76
	v_fmac_f32_e32 v91, v77, v77
	v_fmac_f32_e32 v91, v70, v70
	v_fmac_f32_e32 v91, v71, v71
	v_fmac_f32_e32 v91, v72, v72
	v_fmac_f32_e32 v91, v73, v73
	v_fmac_f32_e32 v91, v66, v66
	v_fmac_f32_e32 v91, v67, v67
	v_fmac_f32_e32 v91, v68, v68
	v_pk_mul_f32 v[98:99], v[82:83], v[82:83]
	v_fmac_f32_e32 v91, v69, v69
	v_add_f32_e32 v91, v91, v98
	v_pk_mul_f32 v[100:101], v[84:85], v[84:85]
	v_add_f32_e32 v91, v99, v91
	v_add_f32_e32 v91, v100, v91
	v_pk_mul_f32 v[102:103], v[86:87], v[86:87]
	v_add_f32_e32 v91, v101, v91
	v_add_f32_e32 v91, v102, v91
	v_pk_mul_f32 v[104:105], v[88:89], v[88:89]
	v_add_f32_e32 v91, v103, v91
	v_add_f32_e32 v91, v104, v91
	v_add_f32_e32 v91, v105, v91
	ds_bpermute_b32 v93, v146, v91
	v_mov_b64_e32 v[98:99], s[24:25]
	v_mov_b32_e32 v127, v163
	s_waitcnt lgkmcnt(0)
	v_add_f32_e32 v91, v91, v93
	ds_bpermute_b32 v93, v149, v91
	s_waitcnt lgkmcnt(0)
	v_add_f32_e32 v91, v91, v93
	v_fmamk_f32 v91, v91, 0x3c2aaaab, v1
	v_mul_f32_e32 v93, 0x4b800000, v91
	v_cmp_gt_f32_e32 vcc, s56, v91
	s_nop 1
	v_cndmask_b32_e32 v91, v91, v93, vcc
	v_rsq_f32_e32 v93, v91
	v_mad_i64_i32 v[90:91], s[30:31], v90, s57, v[98:99]
	v_lshl_add_u64 v[90:91], v[140:141], 1, v[90:91]
	v_mul_f32_e32 v100, 0x45800000, v93
	v_cndmask_b32_e32 v100, v93, v100, vcc
	v_mul_f32_e32 v78, v78, v100
	v_mul_f32_e32 v79, v79, v100
	v_lshl_add_u64 v[98:99], v[90:91], 0, v[126:127]
	v_mul_f32_e32 v80, v80, v100
	v_mul_f32_e32 v81, v81, v100
	v_mul_f32_e32 v74, v74, v100
	v_mul_f32_e32 v75, v75, v100
	v_mul_f32_e32 v76, v76, v100
	v_mul_f32_e32 v77, v77, v100
	v_mul_f32_e32 v70, v70, v100
	v_mul_f32_e32 v71, v71, v100
	v_mul_f32_e32 v72, v72, v100
	v_mul_f32_e32 v73, v73, v100
	v_mul_f32_e32 v66, v66, v100
	v_mul_f32_e32 v67, v67, v100
	v_mul_f32_e32 v68, v68, v100
	v_mul_f32_e32 v69, v69, v100
	s_and_b64 vcc, exec, s[6:7]
	v_mul_f32_e32 v78, v170, v78
	v_mul_f32_e32 v79, v171, v79
	v_mul_f32_e32 v80, v172, v80
	v_mul_f32_e32 v81, v173, v81
	v_cvt_pk_bf16_f32 v78, v78, v79
	v_cvt_pk_bf16_f32 v79, v80, v81
	global_store_dwordx2 v[98:99], v[78:79], off
	v_mul_f32_e32 v74, v174, v74
	v_mul_f32_e32 v75, v175, v75
	v_mul_f32_e32 v76, v176, v76
	v_mul_f32_e32 v77, v177, v77
	v_cvt_pk_bf16_f32 v74, v74, v75
	v_cvt_pk_bf16_f32 v75, v76, v77
	global_store_dwordx2 v[98:99], v[74:75], off offset:32
	v_mul_f32_e32 v70, v178, v70
	v_mul_f32_e32 v71, v179, v71
	v_mul_f32_e32 v72, v180, v72
	v_mul_f32_e32 v73, v73, v181
	v_cvt_pk_bf16_f32 v70, v70, v71
	v_cvt_pk_bf16_f32 v71, v72, v73
	global_store_dwordx2 v[98:99], v[70:71], off offset:64
	v_mul_f32_e32 v66, v66, v182
	v_mul_f32_e32 v67, v67, v183
	v_mul_f32_e32 v68, v68, v184
	v_mul_f32_e32 v69, v69, v185
	v_cvt_pk_bf16_f32 v66, v66, v67
	v_cvt_pk_bf16_f32 v67, v68, v69
	global_store_dwordx2 v[98:99], v[66:67], off offset:96
	s_nop 0
	v_mov_b32_e32 v66, v186
	v_mov_b32_e32 v67, v187
	v_mov_b32_e32 v68, v188
	v_mov_b32_e32 v69, v189
	v_pk_mul_f32 v[66:67], v[100:101], v[66:67] op_sel_hi:[0,1]
	v_pk_mul_f32 v[68:69], v[100:101], v[68:69] op_sel_hi:[0,1]
	v_pk_mul_f32 v[74:75], v[100:101], v[190:191] op_sel_hi:[0,1]
	v_pk_mul_f32 v[76:77], v[100:101], v[192:193] op_sel_hi:[0,1]
	v_pk_mul_f32 v[72:73], v[82:83], v[66:67]
	v_pk_mul_f32 v[70:71], v[84:85], v[68:69]
	v_pk_mul_f32 v[68:69], v[86:87], v[74:75]
	v_pk_mul_f32 v[66:67], v[88:89], v[76:77]
	s_cbranch_vccnz .LBB0_1893
	v_add_u32_e32 v74, s60, v92
	v_ashrrev_i32_e32 v75, 6, v74
	v_and_b32_e32 v74, 63, v74
	v_cndmask_b32_e64 v74, v74, v75, s[4:5]
	v_cvt_f32_i32_e32 v82, v74
	ds_bpermute_b32 v74, v146, v72
	ds_bpermute_b32 v75, v146, v73
	v_mul_f32_e32 v77, 0x3ea1e89b, v82
	v_mul_f32_e32 v78, 0.15915494, v82
	v_mul_f32_e32 v79, 0.15915494, v77
	v_sin_f32_e32 v76, v78
	v_sin_f32_e32 v77, v79
	v_mul_f32_e32 v81, 0x3d0186e3, v82
	v_mul_f32_e32 v84, 0.15915494, v81
	v_cos_f32_e32 v78, v78
	s_waitcnt lgkmcnt(0)
	v_pk_mul_f32 v[74:75], v[76:77], v[74:75]
	v_mul_f32_e32 v77, 0x3dcccccd, v82
	ds_bpermute_b32 v76, v146, v70
	v_mul_f32_e32 v83, 0.15915494, v77
	ds_bpermute_b32 v77, v146, v71
	v_cos_f32_e32 v79, v79
	v_sin_f32_e32 v80, v83
	v_sin_f32_e32 v81, v84
	v_cndmask_b32_e64 v75, v75, -v75, s[2:3]
	v_cndmask_b32_e64 v74, v74, -v74, s[2:3]
	v_pk_fma_f32 v[72:73], v[78:79], v[72:73], v[74:75]
	s_waitcnt lgkmcnt(0)
	v_pk_mul_f32 v[76:77], v[80:81], v[76:77]
	v_mul_f32_e32 v79, 0x3c23d70b, v82
	v_mul_f32_e32 v81, 0x3b4f3e39, v82
	v_cos_f32_e32 v74, v83
	v_cos_f32_e32 v75, v84
	ds_bpermute_b32 v78, v146, v68
	v_mul_f32_e32 v83, 0.15915494, v79
	ds_bpermute_b32 v79, v146, v69
	v_mul_f32_e32 v84, 0.15915494, v81
	v_sin_f32_e32 v80, v83
	v_sin_f32_e32 v81, v84
	v_cndmask_b32_e64 v77, v77, -v77, s[2:3]
	v_cndmask_b32_e64 v76, v76, -v76, s[2:3]
	v_pk_fma_f32 v[70:71], v[74:75], v[70:71], v[76:77]
	v_cos_f32_e32 v74, v83
	v_cos_f32_e32 v75, v84
	s_waitcnt lgkmcnt(0)
	v_pk_mul_f32 v[76:77], v[80:81], v[78:79]
	v_mul_f32_e32 v79, 0x3a831270, v82
	v_mul_f32_e32 v81, 0x39a5cb61, v82
	ds_bpermute_b32 v78, v146, v66
	v_mul_f32_e32 v83, 0.15915494, v79
	ds_bpermute_b32 v79, v146, v67
	v_mul_f32_e32 v82, 0.15915494, v81
	v_sin_f32_e32 v80, v83
	v_sin_f32_e32 v81, v82
	v_cndmask_b32_e64 v77, v77, -v77, s[2:3]
	v_cndmask_b32_e64 v76, v76, -v76, s[2:3]
	v_pk_fma_f32 v[68:69], v[74:75], v[68:69], v[76:77]
	v_cos_f32_e32 v74, v83
	v_cos_f32_e32 v75, v82
	s_waitcnt lgkmcnt(0)
	v_pk_mul_f32 v[76:77], v[80:81], v[78:79]
	s_nop 0
	v_cndmask_b32_e64 v77, v77, -v77, s[2:3]
	v_cndmask_b32_e64 v76, v76, -v76, s[2:3]
	v_pk_fma_f32 v[66:67], v[74:75], v[66:67], v[76:77]
.LBB0_1893:
	s_nop 0
	v_cvt_pk_bf16_f32 v75, v66, v67
	v_lshl_add_u64 v[66:67], v[90:91], 0, v[162:163]
	v_cvt_pk_bf16_f32 v72, v72, v73
	v_cvt_pk_bf16_f32 v73, v70, v71
	v_cvt_pk_bf16_f32 v74, v68, v69
	global_store_dwordx4 v[66:67], v[72:75], off offset:128
	s_cmp_gt_i32 s62, 1
	s_mov_b64 s[30:31], -1
	s_cbranch_scc0 .LBB0_1895
	v_add_u32_e32 v66, 0x140, v148
	v_ashrrev_i32_e32 v67, 31, v66
	v_lshlrev_b64 v[66:67], 7, v[66:67]
	v_lshl_add_u64 v[66:67], s[22:23], 0, v[66:67]
	v_mov_b32_e32 v139, v163
	v_lshl_add_u64 v[66:67], v[66:67], 0, v[138:139]
	s_waitcnt vmcnt(26)
	v_mov_b32_e32 v70, v226
	v_mov_b32_e32 v71, v227
	v_mov_b32_e32 v72, v228
	v_mov_b32_e32 v73, v229
	s_nop 0
	v_mov_b32_e32 v66, v218
	v_mov_b32_e32 v67, v219
	v_mov_b32_e32 v68, v220
	v_mov_b32_e32 v69, v221
	s_mov_b64 s[30:31], 0
.LBB0_1895:
	v_or_b32_e32 v76, 64, v147
	s_andn2_b64 vcc, exec, s[30:31]
	v_add_u32_e32 v74, s61, v76
	s_cbranch_vccnz .LBB0_1899
	s_cmp_lg_u32 s62, 0
	v_mov_b32_e32 v66, v74
	s_cbranch_scc0 .LBB0_1898
	v_add_u32_e32 v66, s63, v76

.LBB0_1899:
	v_mul_f32_e32 v75, v63, v63
	v_fmac_f32_e32 v75, v62, v62
	v_fmac_f32_e32 v75, v64, v64
	v_fmac_f32_e32 v75, v65, v65
	v_fmac_f32_e32 v75, v58, v58
	v_fmac_f32_e32 v75, v59, v59
	v_fmac_f32_e32 v75, v60, v60
	v_fmac_f32_e32 v75, v61, v61
	v_fmac_f32_e32 v75, v54, v54
	v_fmac_f32_e32 v75, v55, v55
	v_fmac_f32_e32 v75, v56, v56
	v_fmac_f32_e32 v75, v57, v57
	v_fmac_f32_e32 v75, v50, v50
	v_fmac_f32_e32 v75, v51, v51
	v_fmac_f32_e32 v75, v52, v52
	v_pk_mul_f32 v[82:83], v[66:67], v[66:67]
	v_fmac_f32_e32 v75, v53, v53
	v_add_f32_e32 v75, v75, v82
	v_pk_mul_f32 v[84:85], v[68:69], v[68:69]
	v_add_f32_e32 v75, v83, v75
	v_add_f32_e32 v75, v84, v75
	v_pk_mul_f32 v[86:87], v[70:71], v[70:71]
	v_add_f32_e32 v75, v85, v75
	v_add_f32_e32 v75, v86, v75
	v_pk_mul_f32 v[88:89], v[72:73], v[72:73]
	v_add_f32_e32 v75, v87, v75
	v_add_f32_e32 v75, v88, v75
	v_add_f32_e32 v75, v89, v75
	ds_bpermute_b32 v77, v146, v75
	v_mov_b64_e32 v[82:83], s[24:25]
	v_mov_b32_e32 v127, v163
	s_waitcnt lgkmcnt(0)
	v_add_f32_e32 v75, v75, v77
	ds_bpermute_b32 v77, v149, v75
	s_waitcnt lgkmcnt(0)
	v_add_f32_e32 v75, v75, v77
	v_fmamk_f32 v75, v75, 0x3c2aaaab, v1
	v_mul_f32_e32 v77, 0x4b800000, v75
	v_cmp_gt_f32_e32 vcc, s56, v75
	s_nop 1
	v_cndmask_b32_e32 v75, v75, v77, vcc
	v_rsq_f32_e32 v77, v75
	v_mad_i64_i32 v[74:75], s[30:31], v74, s57, v[82:83]
	v_lshl_add_u64 v[74:75], v[140:141], 1, v[74:75]
	v_mul_f32_e32 v84, 0x45800000, v77
	v_cndmask_b32_e32 v84, v77, v84, vcc
	v_mul_f32_e32 v62, v62, v84
	v_mul_f32_e32 v63, v63, v84
	v_lshl_add_u64 v[82:83], v[74:75], 0, v[126:127]
	v_mul_f32_e32 v64, v64, v84
	v_mul_f32_e32 v65, v65, v84
	v_mul_f32_e32 v58, v58, v84
	v_mul_f32_e32 v59, v59, v84
	v_mul_f32_e32 v60, v60, v84
	v_mul_f32_e32 v61, v61, v84
	v_mul_f32_e32 v54, v54, v84
	v_mul_f32_e32 v55, v55, v84
	v_mul_f32_e32 v56, v56, v84
	v_mul_f32_e32 v57, v57, v84
	v_mul_f32_e32 v50, v50, v84
	v_mul_f32_e32 v51, v51, v84
	v_mul_f32_e32 v52, v52, v84
	v_mul_f32_e32 v53, v53, v84
	s_and_b64 vcc, exec, s[6:7]
	v_mul_f32_e32 v62, v170, v62
	v_mul_f32_e32 v63, v171, v63
	v_mul_f32_e32 v64, v172, v64
	v_mul_f32_e32 v65, v173, v65
	v_cvt_pk_bf16_f32 v62, v62, v63
	v_cvt_pk_bf16_f32 v63, v64, v65
	global_store_dwordx2 v[82:83], v[62:63], off
	v_mul_f32_e32 v58, v174, v58
	v_mul_f32_e32 v59, v175, v59
	v_mul_f32_e32 v60, v176, v60
	v_mul_f32_e32 v61, v177, v61
	v_cvt_pk_bf16_f32 v58, v58, v59
	v_cvt_pk_bf16_f32 v59, v60, v61
	global_store_dwordx2 v[82:83], v[58:59], off offset:32
	v_mul_f32_e32 v54, v178, v54
	v_mul_f32_e32 v55, v179, v55
	v_mul_f32_e32 v56, v180, v56
	v_mul_f32_e32 v57, v57, v181
	v_cvt_pk_bf16_f32 v54, v54, v55
	v_cvt_pk_bf16_f32 v55, v56, v57
	global_store_dwordx2 v[82:83], v[54:55], off offset:64
	v_mul_f32_e32 v50, v50, v182
	v_mul_f32_e32 v51, v51, v183
	v_mul_f32_e32 v52, v52, v184
	v_mul_f32_e32 v53, v53, v185
	v_cvt_pk_bf16_f32 v50, v50, v51
	v_cvt_pk_bf16_f32 v51, v52, v53
	global_store_dwordx2 v[82:83], v[50:51], off offset:96
	s_nop 0
	v_mov_b32_e32 v50, v186
	v_mov_b32_e32 v51, v187
	v_mov_b32_e32 v52, v188
	v_mov_b32_e32 v53, v189
	v_pk_mul_f32 v[50:51], v[84:85], v[50:51] op_sel_hi:[0,1]
	v_pk_mul_f32 v[52:53], v[84:85], v[52:53] op_sel_hi:[0,1]
	v_pk_mul_f32 v[58:59], v[84:85], v[190:191] op_sel_hi:[0,1]
	v_pk_mul_f32 v[60:61], v[84:85], v[192:193] op_sel_hi:[0,1]
	v_pk_mul_f32 v[56:57], v[66:67], v[50:51]
	v_pk_mul_f32 v[54:55], v[68:69], v[52:53]
	v_pk_mul_f32 v[52:53], v[70:71], v[58:59]
	v_pk_mul_f32 v[50:51], v[72:73], v[60:61]
	s_cbranch_vccnz .LBB0_1901
	v_add_u32_e32 v58, s60, v76
	v_ashrrev_i32_e32 v59, 6, v58
	v_and_b32_e32 v58, 63, v58
	v_cndmask_b32_e64 v58, v58, v59, s[4:5]
	v_cvt_f32_i32_e32 v66, v58
	ds_bpermute_b32 v58, v146, v56
	ds_bpermute_b32 v59, v146, v57
	v_mul_f32_e32 v61, 0x3ea1e89b, v66
	v_mul_f32_e32 v62, 0.15915494, v66
	v_mul_f32_e32 v63, 0.15915494, v61
	v_sin_f32_e32 v60, v62
	v_sin_f32_e32 v61, v63
	v_mul_f32_e32 v65, 0x3d0186e3, v66
	v_mul_f32_e32 v68, 0.15915494, v65
	v_cos_f32_e32 v62, v62
	s_waitcnt lgkmcnt(0)
	v_pk_mul_f32 v[58:59], v[60:61], v[58:59]
	v_mul_f32_e32 v61, 0x3dcccccd, v66
	ds_bpermute_b32 v60, v146, v54
	v_mul_f32_e32 v67, 0.15915494, v61
	ds_bpermute_b32 v61, v146, v55
	v_cos_f32_e32 v63, v63
	v_sin_f32_e32 v64, v67
	v_sin_f32_e32 v65, v68
	v_cndmask_b32_e64 v59, v59, -v59, s[2:3]
	v_cndmask_b32_e64 v58, v58, -v58, s[2:3]
	v_pk_fma_f32 v[56:57], v[62:63], v[56:57], v[58:59]
	s_waitcnt lgkmcnt(0)
	v_pk_mul_f32 v[60:61], v[64:65], v[60:61]
	v_mul_f32_e32 v63, 0x3c23d70b, v66
	v_mul_f32_e32 v65, 0x3b4f3e39, v66
	v_cos_f32_e32 v58, v67
	v_cos_f32_e32 v59, v68
	ds_bpermute_b32 v62, v146, v52
	v_mul_f32_e32 v67, 0.15915494, v63
	ds_bpermute_b32 v63, v146, v53
	v_mul_f32_e32 v68, 0.15915494, v65
	v_sin_f32_e32 v64, v67
	v_sin_f32_e32 v65, v68
	v_cndmask_b32_e64 v61, v61, -v61, s[2:3]
	v_cndmask_b32_e64 v60, v60, -v60, s[2:3]
	v_pk_fma_f32 v[54:55], v[58:59], v[54:55], v[60:61]
	v_cos_f32_e32 v58, v67
	v_cos_f32_e32 v59, v68
	s_waitcnt lgkmcnt(0)
	v_pk_mul_f32 v[60:61], v[64:65], v[62:63]
	v_mul_f32_e32 v63, 0x3a831270, v66
	v_mul_f32_e32 v65, 0x39a5cb61, v66
	ds_bpermute_b32 v62, v146, v50
	v_mul_f32_e32 v67, 0.15915494, v63
	ds_bpermute_b32 v63, v146, v51
	v_mul_f32_e32 v66, 0.15915494, v65
	v_sin_f32_e32 v64, v67
	v_sin_f32_e32 v65, v66
	v_cndmask_b32_e64 v61, v61, -v61, s[2:3]
	v_cndmask_b32_e64 v60, v60, -v60, s[2:3]
	v_pk_fma_f32 v[52:53], v[58:59], v[52:53], v[60:61]
	v_cos_f32_e32 v58, v67
	v_cos_f32_e32 v59, v66
	s_waitcnt lgkmcnt(0)
	v_pk_mul_f32 v[60:61], v[64:65], v[62:63]
	s_nop 0
	v_cndmask_b32_e64 v61, v61, -v61, s[2:3]
	v_cndmask_b32_e64 v60, v60, -v60, s[2:3]
	v_pk_fma_f32 v[50:51], v[58:59], v[50:51], v[60:61]
.LBB0_1901:
	s_nop 0
	v_cvt_pk_bf16_f32 v59, v50, v51
	v_lshl_add_u64 v[50:51], v[74:75], 0, v[162:163]
	v_cvt_pk_bf16_f32 v56, v56, v57
	v_cvt_pk_bf16_f32 v57, v54, v55
	v_cvt_pk_bf16_f32 v58, v52, v53
	global_store_dwordx4 v[50:51], v[56:59], off offset:128
	s_cmp_gt_i32 s62, 1
	s_mov_b64 s[30:31], -1
	s_cbranch_scc0 .LBB0_1903
	v_add_u32_e32 v50, 0x150, v148
	v_ashrrev_i32_e32 v51, 31, v50
	v_lshlrev_b64 v[50:51], 7, v[50:51]
	v_lshl_add_u64 v[50:51], s[22:23], 0, v[50:51]
	v_mov_b32_e32 v139, v163
	v_lshl_add_u64 v[50:51], v[50:51], 0, v[138:139]
	s_waitcnt vmcnt(29)
	v_mov_b32_e32 v54, v234
	v_mov_b32_e32 v55, v235
	v_mov_b32_e32 v56, v236
	v_mov_b32_e32 v57, v237
	s_nop 0
	v_mov_b32_e32 v50, v230
	v_mov_b32_e32 v51, v231
	v_mov_b32_e32 v52, v232
	v_mov_b32_e32 v53, v233
	s_mov_b64 s[30:31], 0
.LBB0_1903:
	v_or_b32_e32 v60, 0x50, v147
	s_andn2_b64 vcc, exec, s[30:31]
	v_add_u32_e32 v58, s61, v60
	s_cbranch_vccnz .LBB0_1907
	s_cmp_lg_u32 s62, 0
	v_mov_b32_e32 v50, v58
	s_cbranch_scc0 .LBB0_1906
	v_add_u32_e32 v50, s63, v60

.LBB0_1907:
	v_mul_f32_e32 v59, v47, v47
	v_fmac_f32_e32 v59, v46, v46
	v_fmac_f32_e32 v59, v48, v48
	v_fmac_f32_e32 v59, v49, v49
	v_fmac_f32_e32 v59, v42, v42
	v_fmac_f32_e32 v59, v43, v43
	v_fmac_f32_e32 v59, v44, v44
	v_fmac_f32_e32 v59, v45, v45
	v_fmac_f32_e32 v59, v38, v38
	v_fmac_f32_e32 v59, v39, v39
	v_fmac_f32_e32 v59, v40, v40
	v_fmac_f32_e32 v59, v41, v41
	v_fmac_f32_e32 v59, v34, v34
	v_fmac_f32_e32 v59, v35, v35
	v_fmac_f32_e32 v59, v36, v36
	v_pk_mul_f32 v[66:67], v[50:51], v[50:51]
	v_fmac_f32_e32 v59, v37, v37
	v_add_f32_e32 v59, v59, v66
	v_pk_mul_f32 v[68:69], v[52:53], v[52:53]
	v_add_f32_e32 v59, v67, v59
	v_add_f32_e32 v59, v68, v59
	v_pk_mul_f32 v[70:71], v[54:55], v[54:55]
	v_add_f32_e32 v59, v69, v59
	v_add_f32_e32 v59, v70, v59
	v_pk_mul_f32 v[72:73], v[56:57], v[56:57]
	v_add_f32_e32 v59, v71, v59
	v_add_f32_e32 v59, v72, v59
	v_add_f32_e32 v59, v73, v59
	ds_bpermute_b32 v61, v146, v59
	v_mov_b64_e32 v[66:67], s[24:25]
	v_mov_b32_e32 v127, v163
	s_waitcnt lgkmcnt(0)
	v_add_f32_e32 v59, v59, v61
	ds_bpermute_b32 v61, v149, v59
	s_waitcnt lgkmcnt(0)
	v_add_f32_e32 v59, v59, v61
	v_fmamk_f32 v59, v59, 0x3c2aaaab, v1
	v_mul_f32_e32 v61, 0x4b800000, v59
	v_cmp_gt_f32_e32 vcc, s56, v59
	s_nop 1
	v_cndmask_b32_e32 v59, v59, v61, vcc
	v_rsq_f32_e32 v61, v59
	v_mad_i64_i32 v[58:59], s[30:31], v58, s57, v[66:67]
	v_lshl_add_u64 v[58:59], v[140:141], 1, v[58:59]
	v_mul_f32_e32 v68, 0x45800000, v61
	v_cndmask_b32_e32 v68, v61, v68, vcc
	v_mul_f32_e32 v46, v46, v68
	v_mul_f32_e32 v47, v47, v68
	v_lshl_add_u64 v[66:67], v[58:59], 0, v[126:127]
	v_mul_f32_e32 v48, v48, v68
	v_mul_f32_e32 v49, v49, v68
	v_mul_f32_e32 v42, v42, v68
	v_mul_f32_e32 v43, v43, v68
	v_mul_f32_e32 v44, v44, v68
	v_mul_f32_e32 v45, v45, v68
	v_mul_f32_e32 v38, v38, v68
	v_mul_f32_e32 v39, v39, v68
	v_mul_f32_e32 v40, v40, v68
	v_mul_f32_e32 v41, v41, v68
	v_mul_f32_e32 v34, v34, v68
	v_mul_f32_e32 v35, v35, v68
	v_mul_f32_e32 v36, v36, v68
	v_mul_f32_e32 v37, v37, v68
	s_and_b64 vcc, exec, s[6:7]
	v_mul_f32_e32 v46, v170, v46
	v_mul_f32_e32 v47, v171, v47
	v_mul_f32_e32 v48, v172, v48
	v_mul_f32_e32 v49, v173, v49
	v_cvt_pk_bf16_f32 v46, v46, v47
	v_cvt_pk_bf16_f32 v47, v48, v49
	global_store_dwordx2 v[66:67], v[46:47], off
	v_mul_f32_e32 v42, v174, v42
	v_mul_f32_e32 v43, v175, v43
	v_mul_f32_e32 v44, v176, v44
	v_mul_f32_e32 v45, v177, v45
	v_cvt_pk_bf16_f32 v42, v42, v43
	v_cvt_pk_bf16_f32 v43, v44, v45
	global_store_dwordx2 v[66:67], v[42:43], off offset:32
	v_mul_f32_e32 v38, v178, v38
	v_mul_f32_e32 v39, v179, v39
	v_mul_f32_e32 v40, v180, v40
	v_mul_f32_e32 v41, v41, v181
	v_cvt_pk_bf16_f32 v38, v38, v39
	v_cvt_pk_bf16_f32 v39, v40, v41
	global_store_dwordx2 v[66:67], v[38:39], off offset:64
	v_mul_f32_e32 v34, v34, v182
	v_mul_f32_e32 v35, v35, v183
	v_mul_f32_e32 v36, v36, v184
	v_mul_f32_e32 v37, v37, v185
	v_cvt_pk_bf16_f32 v34, v34, v35
	v_cvt_pk_bf16_f32 v35, v36, v37
	global_store_dwordx2 v[66:67], v[34:35], off offset:96
	s_nop 0
	v_mov_b32_e32 v34, v186
	v_mov_b32_e32 v35, v187
	v_mov_b32_e32 v36, v188
	v_mov_b32_e32 v37, v189
	v_pk_mul_f32 v[34:35], v[68:69], v[34:35] op_sel_hi:[0,1]
	v_pk_mul_f32 v[36:37], v[68:69], v[36:37] op_sel_hi:[0,1]
	v_pk_mul_f32 v[42:43], v[68:69], v[190:191] op_sel_hi:[0,1]
	v_pk_mul_f32 v[44:45], v[68:69], v[192:193] op_sel_hi:[0,1]
	v_pk_mul_f32 v[40:41], v[50:51], v[34:35]
	v_pk_mul_f32 v[38:39], v[52:53], v[36:37]
	v_pk_mul_f32 v[36:37], v[54:55], v[42:43]
	v_pk_mul_f32 v[34:35], v[56:57], v[44:45]
	s_cbranch_vccnz .LBB0_1909
	v_add_u32_e32 v42, s60, v60
	v_ashrrev_i32_e32 v43, 6, v42
	v_and_b32_e32 v42, 63, v42
	v_cndmask_b32_e64 v42, v42, v43, s[4:5]
	v_cvt_f32_i32_e32 v50, v42
	ds_bpermute_b32 v42, v146, v40
	ds_bpermute_b32 v43, v146, v41
	v_mul_f32_e32 v45, 0x3ea1e89b, v50
	v_mul_f32_e32 v46, 0.15915494, v50
	v_mul_f32_e32 v47, 0.15915494, v45
	v_sin_f32_e32 v44, v46
	v_sin_f32_e32 v45, v47
	v_mul_f32_e32 v49, 0x3d0186e3, v50
	v_mul_f32_e32 v52, 0.15915494, v49
	v_cos_f32_e32 v46, v46
	s_waitcnt lgkmcnt(0)
	v_pk_mul_f32 v[42:43], v[44:45], v[42:43]
	v_mul_f32_e32 v45, 0x3dcccccd, v50
	ds_bpermute_b32 v44, v146, v38
	v_mul_f32_e32 v51, 0.15915494, v45
	ds_bpermute_b32 v45, v146, v39
	v_cos_f32_e32 v47, v47
	v_sin_f32_e32 v48, v51
	v_sin_f32_e32 v49, v52
	v_cndmask_b32_e64 v43, v43, -v43, s[2:3]
	v_cndmask_b32_e64 v42, v42, -v42, s[2:3]
	v_pk_fma_f32 v[40:41], v[46:47], v[40:41], v[42:43]
	s_waitcnt lgkmcnt(0)
	v_pk_mul_f32 v[44:45], v[48:49], v[44:45]
	v_mul_f32_e32 v47, 0x3c23d70b, v50
	v_mul_f32_e32 v49, 0x3b4f3e39, v50
	v_cos_f32_e32 v42, v51
	v_cos_f32_e32 v43, v52
	ds_bpermute_b32 v46, v146, v36
	v_mul_f32_e32 v51, 0.15915494, v47
	ds_bpermute_b32 v47, v146, v37
	v_mul_f32_e32 v52, 0.15915494, v49
	v_sin_f32_e32 v48, v51
	v_sin_f32_e32 v49, v52
	v_cndmask_b32_e64 v45, v45, -v45, s[2:3]
	v_cndmask_b32_e64 v44, v44, -v44, s[2:3]
	v_pk_fma_f32 v[38:39], v[42:43], v[38:39], v[44:45]
	v_cos_f32_e32 v42, v51
	v_cos_f32_e32 v43, v52
	s_waitcnt lgkmcnt(0)
	v_pk_mul_f32 v[44:45], v[48:49], v[46:47]
	v_mul_f32_e32 v47, 0x3a831270, v50
	v_mul_f32_e32 v49, 0x39a5cb61, v50
	ds_bpermute_b32 v46, v146, v34
	v_mul_f32_e32 v51, 0.15915494, v47
	ds_bpermute_b32 v47, v146, v35
	v_mul_f32_e32 v50, 0.15915494, v49
	v_sin_f32_e32 v48, v51
	v_sin_f32_e32 v49, v50
	v_cndmask_b32_e64 v45, v45, -v45, s[2:3]
	v_cndmask_b32_e64 v44, v44, -v44, s[2:3]
	v_pk_fma_f32 v[36:37], v[42:43], v[36:37], v[44:45]
	v_cos_f32_e32 v42, v51
	v_cos_f32_e32 v43, v50
	s_waitcnt lgkmcnt(0)
	v_pk_mul_f32 v[44:45], v[48:49], v[46:47]
	s_nop 0
	v_cndmask_b32_e64 v45, v45, -v45, s[2:3]
	v_cndmask_b32_e64 v44, v44, -v44, s[2:3]
	v_pk_fma_f32 v[34:35], v[42:43], v[34:35], v[44:45]
.LBB0_1909:
	s_nop 0
	v_cvt_pk_bf16_f32 v43, v34, v35
	v_lshl_add_u64 v[34:35], v[58:59], 0, v[162:163]
	v_cvt_pk_bf16_f32 v40, v40, v41
	v_cvt_pk_bf16_f32 v41, v38, v39
	v_cvt_pk_bf16_f32 v42, v36, v37
	global_store_dwordx4 v[34:35], v[40:43], off offset:128
	s_cmp_gt_i32 s62, 1
	s_mov_b64 s[30:31], -1
	s_cbranch_scc0 .LBB0_1911
	v_add_u32_e32 v34, 0x160, v148
	v_ashrrev_i32_e32 v35, 31, v34
	v_lshlrev_b64 v[34:35], 7, v[34:35]
	v_lshl_add_u64 v[34:35], s[22:23], 0, v[34:35]
	v_mov_b32_e32 v139, v163
	v_lshl_add_u64 v[34:35], v[34:35], 0, v[138:139]
	s_waitcnt vmcnt(32)
	v_mov_b32_e32 v38, v242
	v_mov_b32_e32 v39, v243
	v_mov_b32_e32 v40, v244
	v_mov_b32_e32 v41, v245
	s_nop 0
	v_mov_b32_e32 v34, v238
	v_mov_b32_e32 v35, v239
	v_mov_b32_e32 v36, v240
	v_mov_b32_e32 v37, v241
	s_mov_b64 s[30:31], 0
.LBB0_1911:
	v_or_b32_e32 v44, 0x60, v147
	s_andn2_b64 vcc, exec, s[30:31]
	v_add_u32_e32 v42, s61, v44
	s_cbranch_vccnz .LBB0_1915
	s_cmp_lg_u32 s62, 0
	v_mov_b32_e32 v34, v42
	s_cbranch_scc0 .LBB0_1914
	v_add_u32_e32 v34, s63, v44

.LBB0_1915:
	v_mul_f32_e32 v43, v31, v31
	v_fmac_f32_e32 v43, v30, v30
	v_fmac_f32_e32 v43, v32, v32
	v_fmac_f32_e32 v43, v33, v33
	v_fmac_f32_e32 v43, v26, v26
	v_fmac_f32_e32 v43, v27, v27
	v_fmac_f32_e32 v43, v28, v28
	v_fmac_f32_e32 v43, v29, v29
	v_fmac_f32_e32 v43, v22, v22
	v_fmac_f32_e32 v43, v23, v23
	v_fmac_f32_e32 v43, v24, v24
	v_fmac_f32_e32 v43, v25, v25
	v_fmac_f32_e32 v43, v18, v18
	v_fmac_f32_e32 v43, v19, v19
	v_fmac_f32_e32 v43, v20, v20
	v_pk_mul_f32 v[50:51], v[34:35], v[34:35]
	v_fmac_f32_e32 v43, v21, v21
	v_add_f32_e32 v43, v43, v50
	v_pk_mul_f32 v[52:53], v[36:37], v[36:37]
	v_add_f32_e32 v43, v51, v43
	v_add_f32_e32 v43, v52, v43
	v_pk_mul_f32 v[54:55], v[38:39], v[38:39]
	v_add_f32_e32 v43, v53, v43
	v_add_f32_e32 v43, v54, v43
	v_pk_mul_f32 v[56:57], v[40:41], v[40:41]
	v_add_f32_e32 v43, v55, v43
	v_add_f32_e32 v43, v56, v43
	v_add_f32_e32 v43, v57, v43
	ds_bpermute_b32 v45, v146, v43
	v_mov_b64_e32 v[50:51], s[24:25]
	v_mov_b32_e32 v127, v163
	s_waitcnt lgkmcnt(0)
	v_add_f32_e32 v43, v43, v45
	ds_bpermute_b32 v45, v149, v43
	s_waitcnt lgkmcnt(0)
	v_add_f32_e32 v43, v43, v45
	v_fmamk_f32 v43, v43, 0x3c2aaaab, v1
	v_mul_f32_e32 v45, 0x4b800000, v43
	v_cmp_gt_f32_e32 vcc, s56, v43
	s_nop 1
	v_cndmask_b32_e32 v43, v43, v45, vcc
	v_rsq_f32_e32 v45, v43
	v_mad_i64_i32 v[42:43], s[30:31], v42, s57, v[50:51]
	v_lshl_add_u64 v[42:43], v[140:141], 1, v[42:43]
	v_mul_f32_e32 v52, 0x45800000, v45
	v_cndmask_b32_e32 v52, v45, v52, vcc
	v_mul_f32_e32 v30, v30, v52
	v_mul_f32_e32 v31, v31, v52
	v_lshl_add_u64 v[50:51], v[42:43], 0, v[126:127]
	v_mul_f32_e32 v32, v32, v52
	v_mul_f32_e32 v33, v33, v52
	v_mul_f32_e32 v26, v26, v52
	v_mul_f32_e32 v27, v27, v52
	v_mul_f32_e32 v28, v28, v52
	v_mul_f32_e32 v29, v29, v52
	v_mul_f32_e32 v22, v22, v52
	v_mul_f32_e32 v23, v23, v52
	v_mul_f32_e32 v24, v24, v52
	v_mul_f32_e32 v25, v25, v52
	v_mul_f32_e32 v18, v18, v52
	v_mul_f32_e32 v19, v19, v52
	v_mul_f32_e32 v20, v20, v52
	v_mul_f32_e32 v21, v21, v52
	s_and_b64 vcc, exec, s[6:7]
	v_mul_f32_e32 v30, v170, v30
	v_mul_f32_e32 v31, v171, v31
	v_mul_f32_e32 v32, v172, v32
	v_mul_f32_e32 v33, v173, v33
	v_cvt_pk_bf16_f32 v30, v30, v31
	v_cvt_pk_bf16_f32 v31, v32, v33
	global_store_dwordx2 v[50:51], v[30:31], off
	v_mul_f32_e32 v26, v174, v26
	v_mul_f32_e32 v27, v175, v27
	v_mul_f32_e32 v28, v176, v28
	v_mul_f32_e32 v29, v177, v29
	v_cvt_pk_bf16_f32 v26, v26, v27
	v_cvt_pk_bf16_f32 v27, v28, v29
	global_store_dwordx2 v[50:51], v[26:27], off offset:32
	v_mul_f32_e32 v22, v178, v22
	v_mul_f32_e32 v23, v179, v23
	v_mul_f32_e32 v24, v180, v24
	v_mul_f32_e32 v25, v25, v181
	v_cvt_pk_bf16_f32 v22, v22, v23
	v_cvt_pk_bf16_f32 v23, v24, v25
	global_store_dwordx2 v[50:51], v[22:23], off offset:64
	v_mul_f32_e32 v18, v18, v182
	v_mul_f32_e32 v19, v19, v183
	v_mul_f32_e32 v20, v20, v184
	v_mul_f32_e32 v21, v21, v185
	v_cvt_pk_bf16_f32 v18, v18, v19
	v_cvt_pk_bf16_f32 v19, v20, v21
	global_store_dwordx2 v[50:51], v[18:19], off offset:96
	s_nop 0
	v_mov_b32_e32 v18, v186
	v_mov_b32_e32 v19, v187
	v_mov_b32_e32 v20, v188
	v_mov_b32_e32 v21, v189
	v_pk_mul_f32 v[18:19], v[52:53], v[18:19] op_sel_hi:[0,1]
	v_pk_mul_f32 v[20:21], v[52:53], v[20:21] op_sel_hi:[0,1]
	v_pk_mul_f32 v[26:27], v[52:53], v[190:191] op_sel_hi:[0,1]
	v_pk_mul_f32 v[28:29], v[52:53], v[192:193] op_sel_hi:[0,1]
	v_pk_mul_f32 v[24:25], v[34:35], v[18:19]
	v_pk_mul_f32 v[22:23], v[36:37], v[20:21]
	v_pk_mul_f32 v[20:21], v[38:39], v[26:27]
	v_pk_mul_f32 v[18:19], v[40:41], v[28:29]
	s_cbranch_vccnz .LBB0_1917
	v_add_u32_e32 v26, s60, v44
	v_ashrrev_i32_e32 v27, 6, v26
	v_and_b32_e32 v26, 63, v26
	v_cndmask_b32_e64 v26, v26, v27, s[4:5]
	v_cvt_f32_i32_e32 v34, v26
	ds_bpermute_b32 v26, v146, v24
	ds_bpermute_b32 v27, v146, v25
	v_mul_f32_e32 v29, 0x3ea1e89b, v34
	v_mul_f32_e32 v30, 0.15915494, v34
	v_mul_f32_e32 v31, 0.15915494, v29
	v_sin_f32_e32 v28, v30
	v_sin_f32_e32 v29, v31
	v_mul_f32_e32 v33, 0x3d0186e3, v34
	v_mul_f32_e32 v36, 0.15915494, v33
	v_cos_f32_e32 v30, v30
	s_waitcnt lgkmcnt(0)
	v_pk_mul_f32 v[26:27], v[28:29], v[26:27]
	v_mul_f32_e32 v29, 0x3dcccccd, v34
	ds_bpermute_b32 v28, v146, v22
	v_mul_f32_e32 v35, 0.15915494, v29
	ds_bpermute_b32 v29, v146, v23
	v_cos_f32_e32 v31, v31
	v_sin_f32_e32 v32, v35
	v_sin_f32_e32 v33, v36
	v_cndmask_b32_e64 v27, v27, -v27, s[2:3]
	v_cndmask_b32_e64 v26, v26, -v26, s[2:3]
	v_pk_fma_f32 v[24:25], v[30:31], v[24:25], v[26:27]
	s_waitcnt lgkmcnt(0)
	v_pk_mul_f32 v[28:29], v[32:33], v[28:29]
	v_mul_f32_e32 v31, 0x3c23d70b, v34
	v_mul_f32_e32 v33, 0x3b4f3e39, v34
	v_cos_f32_e32 v26, v35
	v_cos_f32_e32 v27, v36
	ds_bpermute_b32 v30, v146, v20
	v_mul_f32_e32 v35, 0.15915494, v31
	ds_bpermute_b32 v31, v146, v21
	v_mul_f32_e32 v36, 0.15915494, v33
	v_sin_f32_e32 v32, v35
	v_sin_f32_e32 v33, v36
	v_cndmask_b32_e64 v29, v29, -v29, s[2:3]
	v_cndmask_b32_e64 v28, v28, -v28, s[2:3]
	v_pk_fma_f32 v[22:23], v[26:27], v[22:23], v[28:29]
	v_cos_f32_e32 v26, v35
	v_cos_f32_e32 v27, v36
	s_waitcnt lgkmcnt(0)
	v_pk_mul_f32 v[28:29], v[32:33], v[30:31]
	v_mul_f32_e32 v31, 0x3a831270, v34
	v_mul_f32_e32 v33, 0x39a5cb61, v34
	ds_bpermute_b32 v30, v146, v18
	v_mul_f32_e32 v35, 0.15915494, v31
	ds_bpermute_b32 v31, v146, v19
	v_mul_f32_e32 v34, 0.15915494, v33
	v_sin_f32_e32 v32, v35
	v_sin_f32_e32 v33, v34
	v_cndmask_b32_e64 v29, v29, -v29, s[2:3]
	v_cndmask_b32_e64 v28, v28, -v28, s[2:3]
	v_pk_fma_f32 v[20:21], v[26:27], v[20:21], v[28:29]
	v_cos_f32_e32 v26, v35
	v_cos_f32_e32 v27, v34
	s_waitcnt lgkmcnt(0)
	v_pk_mul_f32 v[28:29], v[32:33], v[30:31]
	s_nop 0
	v_cndmask_b32_e64 v29, v29, -v29, s[2:3]
	v_cndmask_b32_e64 v28, v28, -v28, s[2:3]
	v_pk_fma_f32 v[18:19], v[26:27], v[18:19], v[28:29]
.LBB0_1917:
	s_nop 0
	v_cvt_pk_bf16_f32 v27, v18, v19
	v_lshl_add_u64 v[18:19], v[42:43], 0, v[162:163]
	v_cvt_pk_bf16_f32 v24, v24, v25
	v_cvt_pk_bf16_f32 v25, v22, v23
	v_cvt_pk_bf16_f32 v26, v20, v21
	global_store_dwordx4 v[18:19], v[24:27], off offset:128
	s_cmp_gt_i32 s62, 1
	s_mov_b64 s[30:31], -1
	s_cbranch_scc0 .LBB0_1919
	v_add_u32_e32 v18, 0x170, v148
	v_ashrrev_i32_e32 v19, 31, v18
	v_lshlrev_b64 v[18:19], 7, v[18:19]
	v_lshl_add_u64 v[18:19], s[22:23], 0, v[18:19]
	v_mov_b32_e32 v139, v163
	v_lshl_add_u64 v[18:19], v[18:19], 0, v[138:139]
	s_waitcnt vmcnt(35)
	v_mov_b32_e32 v22, v250
	v_mov_b32_e32 v23, v251
	v_mov_b32_e32 v24, v252
	v_mov_b32_e32 v25, v253
	s_nop 0
	v_mov_b32_e32 v18, v246
	v_mov_b32_e32 v19, v247
	v_mov_b32_e32 v20, v248
	v_mov_b32_e32 v21, v249
	s_mov_b64 s[30:31], 0
.LBB0_1919:
	v_or_b32_e32 v28, 0x70, v147
	s_andn2_b64 vcc, exec, s[30:31]
	v_add_u32_e32 v26, s61, v28
	s_cbranch_vccnz .LBB0_1923
	s_cmp_lg_u32 s62, 0
	v_mov_b32_e32 v18, v26
	s_cbranch_scc0 .LBB0_1922
	v_add_u32_e32 v18, s63, v28

.LBB0_1923:
	v_mul_f32_e32 v27, v15, v15
	v_fmac_f32_e32 v27, v14, v14
	v_fmac_f32_e32 v27, v16, v16
	v_fmac_f32_e32 v27, v17, v17
	v_fmac_f32_e32 v27, v10, v10
	v_fmac_f32_e32 v27, v11, v11
	v_fmac_f32_e32 v27, v12, v12
	v_fmac_f32_e32 v27, v13, v13
	v_fmac_f32_e32 v27, v6, v6
	v_fmac_f32_e32 v27, v7, v7
	v_fmac_f32_e32 v27, v8, v8
	v_fmac_f32_e32 v27, v9, v9
	v_fmac_f32_e32 v27, v2, v2
	v_fmac_f32_e32 v27, v3, v3
	v_fmac_f32_e32 v27, v4, v4
	v_pk_mul_f32 v[34:35], v[18:19], v[18:19]
	v_fmac_f32_e32 v27, v5, v5
	v_add_f32_e32 v27, v27, v34
	v_pk_mul_f32 v[36:37], v[20:21], v[20:21]
	v_add_f32_e32 v27, v35, v27
	v_add_f32_e32 v27, v36, v27
	v_pk_mul_f32 v[38:39], v[22:23], v[22:23]
	v_add_f32_e32 v27, v37, v27
	v_add_f32_e32 v27, v38, v27
	v_pk_mul_f32 v[40:41], v[24:25], v[24:25]
	v_add_f32_e32 v27, v39, v27
	v_add_f32_e32 v27, v40, v27
	v_add_f32_e32 v27, v41, v27
	ds_bpermute_b32 v29, v146, v27
	v_mov_b64_e32 v[34:35], s[24:25]
	v_mov_b32_e32 v127, v163
	s_waitcnt lgkmcnt(0)
	v_add_f32_e32 v27, v27, v29
	ds_bpermute_b32 v29, v149, v27
	s_waitcnt lgkmcnt(0)
	v_add_f32_e32 v27, v27, v29
	v_fmamk_f32 v27, v27, 0x3c2aaaab, v1
	v_mul_f32_e32 v29, 0x4b800000, v27
	v_cmp_gt_f32_e32 vcc, s56, v27
	s_nop 1
	v_cndmask_b32_e32 v27, v27, v29, vcc
	v_rsq_f32_e32 v29, v27
	v_mad_i64_i32 v[26:27], s[30:31], v26, s57, v[34:35]
	v_lshl_add_u64 v[26:27], v[140:141], 1, v[26:27]
	v_mul_f32_e32 v36, 0x45800000, v29
	v_cndmask_b32_e32 v36, v29, v36, vcc
	v_mul_f32_e32 v14, v14, v36
	v_mul_f32_e32 v15, v15, v36
	v_lshl_add_u64 v[34:35], v[26:27], 0, v[126:127]
	v_mul_f32_e32 v16, v16, v36
	v_mul_f32_e32 v17, v17, v36
	v_mul_f32_e32 v10, v10, v36
	v_mul_f32_e32 v11, v11, v36
	v_mul_f32_e32 v12, v12, v36
	v_mul_f32_e32 v13, v13, v36
	v_mul_f32_e32 v6, v6, v36
	v_mul_f32_e32 v7, v7, v36
	v_mul_f32_e32 v8, v8, v36
	v_mul_f32_e32 v9, v9, v36
	v_mul_f32_e32 v2, v2, v36
	v_mul_f32_e32 v3, v3, v36
	v_mul_f32_e32 v4, v4, v36
	v_mul_f32_e32 v5, v5, v36
	s_and_b64 vcc, exec, s[6:7]
	v_mul_f32_e32 v14, v170, v14
	v_mul_f32_e32 v15, v171, v15
	v_mul_f32_e32 v16, v172, v16
	v_mul_f32_e32 v17, v173, v17
	v_cvt_pk_bf16_f32 v14, v14, v15
	v_cvt_pk_bf16_f32 v15, v16, v17
	global_store_dwordx2 v[34:35], v[14:15], off
	v_mul_f32_e32 v10, v174, v10
	v_mul_f32_e32 v11, v175, v11
	v_mul_f32_e32 v12, v176, v12
	v_mul_f32_e32 v13, v177, v13
	v_cvt_pk_bf16_f32 v10, v10, v11
	v_cvt_pk_bf16_f32 v11, v12, v13
	global_store_dwordx2 v[34:35], v[10:11], off offset:32
	v_mul_f32_e32 v6, v178, v6
	v_mul_f32_e32 v7, v179, v7
	v_mul_f32_e32 v8, v180, v8
	v_mul_f32_e32 v9, v9, v181
	v_cvt_pk_bf16_f32 v6, v6, v7
	v_cvt_pk_bf16_f32 v7, v8, v9
	global_store_dwordx2 v[34:35], v[6:7], off offset:64
	v_mul_f32_e32 v2, v2, v182
	v_mul_f32_e32 v3, v3, v183
	v_mul_f32_e32 v4, v4, v184
	v_mul_f32_e32 v5, v5, v185
	v_cvt_pk_bf16_f32 v2, v2, v3
	v_cvt_pk_bf16_f32 v3, v4, v5
	global_store_dwordx2 v[34:35], v[2:3], off offset:96
	s_nop 0
	v_mov_b32_e32 v2, v186
	v_mov_b32_e32 v3, v187
	v_mov_b32_e32 v4, v188
	v_mov_b32_e32 v5, v189
	v_pk_mul_f32 v[2:3], v[36:37], v[2:3] op_sel_hi:[0,1]
	v_pk_mul_f32 v[4:5], v[36:37], v[4:5] op_sel_hi:[0,1]
	v_pk_mul_f32 v[10:11], v[36:37], v[190:191] op_sel_hi:[0,1]
	v_pk_mul_f32 v[12:13], v[36:37], v[192:193] op_sel_hi:[0,1]
	v_pk_mul_f32 v[8:9], v[18:19], v[2:3]
	v_pk_mul_f32 v[6:7], v[20:21], v[4:5]
	v_pk_mul_f32 v[4:5], v[22:23], v[10:11]
	v_pk_mul_f32 v[2:3], v[24:25], v[12:13]
	s_cbranch_vccnz .LBB0_1925
	v_add_u32_e32 v10, s60, v28
	v_ashrrev_i32_e32 v11, 6, v10
	v_and_b32_e32 v10, 63, v10
	v_cndmask_b32_e64 v10, v10, v11, s[4:5]
	v_cvt_f32_i32_e32 v18, v10
	ds_bpermute_b32 v10, v146, v8
	ds_bpermute_b32 v11, v146, v9
	v_mul_f32_e32 v13, 0x3ea1e89b, v18
	v_mul_f32_e32 v14, 0.15915494, v18
	v_mul_f32_e32 v15, 0.15915494, v13
	v_sin_f32_e32 v12, v14
	v_sin_f32_e32 v13, v15
	v_mul_f32_e32 v17, 0x3d0186e3, v18
	v_mul_f32_e32 v20, 0.15915494, v17
	v_cos_f32_e32 v14, v14
	s_waitcnt lgkmcnt(0)
	v_pk_mul_f32 v[10:11], v[12:13], v[10:11]
	v_mul_f32_e32 v13, 0x3dcccccd, v18
	ds_bpermute_b32 v12, v146, v6
	v_mul_f32_e32 v19, 0.15915494, v13
	ds_bpermute_b32 v13, v146, v7
	v_cos_f32_e32 v15, v15
	v_sin_f32_e32 v16, v19
	v_sin_f32_e32 v17, v20
	v_cndmask_b32_e64 v11, v11, -v11, s[2:3]
	v_cndmask_b32_e64 v10, v10, -v10, s[2:3]
	v_pk_fma_f32 v[8:9], v[14:15], v[8:9], v[10:11]
	s_waitcnt lgkmcnt(0)
	v_pk_mul_f32 v[12:13], v[16:17], v[12:13]
	v_mul_f32_e32 v15, 0x3c23d70b, v18
	v_mul_f32_e32 v17, 0x3b4f3e39, v18
	v_cos_f32_e32 v10, v19
	v_cos_f32_e32 v11, v20
	ds_bpermute_b32 v14, v146, v4
	v_mul_f32_e32 v19, 0.15915494, v15
	ds_bpermute_b32 v15, v146, v5
	v_mul_f32_e32 v20, 0.15915494, v17
	v_sin_f32_e32 v16, v19
	v_sin_f32_e32 v17, v20
	v_cndmask_b32_e64 v13, v13, -v13, s[2:3]
	v_cndmask_b32_e64 v12, v12, -v12, s[2:3]
	v_pk_fma_f32 v[6:7], v[10:11], v[6:7], v[12:13]
	v_cos_f32_e32 v10, v19
	v_cos_f32_e32 v11, v20
	s_waitcnt lgkmcnt(0)
	v_pk_mul_f32 v[12:13], v[16:17], v[14:15]
	v_mul_f32_e32 v15, 0x3a831270, v18
	v_mul_f32_e32 v17, 0x39a5cb61, v18
	ds_bpermute_b32 v14, v146, v2
	v_mul_f32_e32 v19, 0.15915494, v15
	ds_bpermute_b32 v15, v146, v3
	v_mul_f32_e32 v18, 0.15915494, v17
	v_sin_f32_e32 v16, v19
	v_sin_f32_e32 v17, v18
	v_cndmask_b32_e64 v13, v13, -v13, s[2:3]
	v_cndmask_b32_e64 v12, v12, -v12, s[2:3]
	v_pk_fma_f32 v[4:5], v[10:11], v[4:5], v[12:13]
	v_cos_f32_e32 v10, v19
	v_cos_f32_e32 v11, v18
	s_waitcnt lgkmcnt(0)
	v_pk_mul_f32 v[12:13], v[16:17], v[14:15]
	s_nop 0
	v_cndmask_b32_e64 v13, v13, -v13, s[2:3]
	v_cndmask_b32_e64 v12, v12, -v12, s[2:3]
	v_pk_fma_f32 v[2:3], v[10:11], v[2:3], v[12:13]
